# GQA loop: K/V DMA two tiles ahead (counted vmcnt), DMA via scalar base, V LDS image in natural key order so P needs no permlane swaps, row-sum cross-half reduction deferred to loop exit
# baseline (speedup 1.0000x reference)
; __device__ __forceinline__ int v_rd_base(int lane) { return ((lane & 3) << 3) | (((lane >> 2) & 3) << 6) | (((lane >> 4) & 1) << 5) | (((lane >> 5) & 1) << 8); }
; template <bool NA, int ROWB>
; __device__ __forceinline__ void attn_dma(const bf16* __restrict__ Qb, const bf16* __restrict__ Kh, const bf16* __restrict__ Vh, bf16* __restrict__ Ob, int NT, char* lds, const int tid, float* __restrict__ ssb, int qrow0, int kr_lo, const float* bl) {
;   const int wid = tid >> 6, lane = tid & 63, r32 = lane & 31, hi = lane >> 5;
;   const int wid_s = __builtin_amdgcn_readfirstlane(wid);
;   char* V_lds = lds; char* K_lds = lds + 3 * SHM_V;
;   float* li_l = (float*)(lds + 3 * SHM_V + 3 * SHM_K) + wid * 64;
;   float* al_l = li_l + 32;
;   float m_reg = -1e30f, l_reg = 0; f32x16 o[4] = {}; bf16x8 qr[8];
;   const int qrow = qrow0 + (wid >> 1), qc = 32 * (wid & 1) + r32;
;   const int c0 = min(max(qc - 8, 0), 48), r0 = min(max(qrow - 4, 0), 120);
;   const bf16* Qw = Qb + (long)(wid * QBLK + r32) * LDQ + hi * 8;
; #pragma unroll
;   for (int d0 = 0; d0 < 8; ++d0) qr[d0] = *reinterpret_cast<const bf16x8*>(Qw + d0 * 16);
;   const int vb0 = (int)(uintptr_t)V_lds + v_rd_base(lane);
;   auto src_off = [&](int i, unsigned& ko, unsigned& vo) __attribute__((always_inline)) {
;     const int b = (wid * 2 + i) * 1024 + lane * 16;
;     { const int row = b >> 8, cb = (b & 255) ^ ((row & 7) << 4); ko = (unsigned)(row * ROWB + cb); }
;     { const int st = b >> 9, within = b & 511, kk = (st >> 2) * 8 + (within >> 6), c = (st & 3) * 32 + ((within & 63) >> 1);
;       const int k = (kk & ~0xC) | ((kk & 4) << 1) | ((kk & 8) >> 1); vo = (unsigned)(k * ROWB + c * 2); }
;   };
;   unsigned ksrc[2], vsrc[2];
;   if constexpr (!NA) { src_off(0, ksrc[0], vsrc[0]); src_off(1, ksrc[1], vsrc[1]); }
.LBB0_100:
	s_andn2_b64 vcc, exec, s[4:5]
	s_cbranch_vccnz .LBB0_125
	v_readlane_b32 s0, v254, 26
	s_cmp_eq_u32 s0, 5
	s_cbranch_scc0 .LBB0_125
	v_readlane_b32 s0, v253, 25
	v_readlane_b32 s1, v253, 26
	s_andn2_b64 vcc, exec, s[0:1]
	s_cbranch_vccnz .LBB0_125
	v_ashrrev_i32_e32 v184, 6, v200
	v_and_b32_e32 v1, 31, v200
	v_lshlrev_b32_e32 v0, 5, v184
	v_or_b32_e32 v2, v0, v1
	s_movk_i32 s0, 0x2400
	v_lshlrev_b32_e32 v6, 4, v202
	v_mad_i64_i32 v[162:163], s[0:1], v2, s0, 0
	v_lshlrev_b32_e32 v5, 3, v202
	v_and_b32_e32 v7, 0xc0, v6
	v_lshlrev_b32_e32 v8, 1, v202
	v_and_or_b32 v7, v5, 24, v7
	v_and_b32_e32 v9, 32, v8
	v_and_b32_e32 v5, 0x100, v5
	v_and_b32_e32 v10, 48, v200
	s_movk_i32 s0, 0xf0
	v_or3_b32 v5, v7, v9, v5
	v_lshl_or_b32 v7, v184, 11, v6
	v_bitop3_b32 v10, v6, v10, s0 bitop3:0x6c
	s_movk_i32 s0, 0xfb00
	v_and_or_b32 v164, v7, s0, v10
	v_ashrrev_i32_e32 v10, 8, v7
	v_bfe_u32 v11, v202, 2, 2
	v_and_b32_e32 v12, 0xfffff0, v10
	v_lshrrev_b32_e32 v13, 2, v202
	v_and_b32_e32 v10, 8, v10
	v_and_or_b32 v11, v13, 4, v11
	v_or3_b32 v10, v12, v10, v11
	v_and_b32_e32 v9, 0xf0, v6
	v_and_b32_e32 v8, 64, v8
	v_and_b32_e32 v6, 48, v6
	v_lshlrev_b32_e32 v10, 8, v10
	v_or_b32_e32 v7, 0x400, v7
	v_or3_b32 v166, v10, v8, v6
	v_lshrrev_b32_e32 v8, 4, v7
	s_movk_i32 s0, 0x70
	v_bitop3_b32 v8, v8, v9, s0 bitop3:0x6c
	s_movk_i32 s0, 0xff00
	v_and_or_b32 v168, v7, s0, v8
	v_ashrrev_i32_e32 v8, 8, v7
	v_and_b32_e32 v9, 0xfffff0, v8
	v_and_b32_e32 v8, 8, v8
	v_lshrrev_b32_e32 v3, 5, v202
	v_and_b32_e32 v4, 0x3fffffc0, v200
	v_lshrrev_b32_e32 v7, 3, v7
	v_or3_b32 v8, v9, v8, v11
	s_add_i32 s0, 0, 0x18000
	v_and_b32_e32 v7, 0xc0, v7
	v_lshlrev_b32_e32 v8, 8, v8
	v_lshl_add_u32 v185, v4, 2, s0
	v_lshlrev_b32_e32 v186, 4, v3
	v_lshlrev_b32_e32 v4, 4, v200
	v_lshlrev_b32_e32 v2, 3, v3
	v_or3_b32 v170, v8, v7, v6
	v_lshlrev_b32_e32 v3, 8, v1
	v_and_b32_e32 v4, 0x70, v4
	v_or_b32_e32 v6, 32, v186
	v_bitop3_b32 v188, v6, v3, v4 bitop3:0xde
	v_or_b32_e32 v6, 64, v186
	v_bitop3_b32 v189, v6, v3, v4 bitop3:0xde
	v_or_b32_e32 v6, 0x60, v186
	v_bitop3_b32 v190, v6, v3, v4 bitop3:0xde
	v_or_b32_e32 v6, 0x80, v186
	v_bitop3_b32 v191, v6, v3, v4 bitop3:0xde
	v_or_b32_e32 v6, 0xa0, v186
	s_cmp_lg_u32 0, -1
	v_bitop3_b32 v192, v6, v3, v4 bitop3:0xde
	v_or_b32_e32 v6, 0xc0, v186
	s_cselect_b32 s0, 0, 0
	v_bitop3_b32 v193, v6, v3, v4 bitop3:0xde
	v_or_b32_e32 v6, 0xe0, v186
	v_add_u32_e32 v195, s0, v5
	s_addk_i32 s0, 0x4000
	v_lshl_add_u32 v204, v1, 2, v185
	v_ashrrev_i32_e32 v1, 31, v0
	v_readlane_b32 s23, v252, 0
	v_mov_b32_e32 v165, v113
	v_mov_b32_e32 v167, v113
	v_mov_b32_e32 v169, v113
	v_mov_b32_e32 v171, v113
	v_bitop3_b32 v187, v186, v3, v4 bitop3:0xde
	v_bitop3_b32 v194, v6, v3, v4 bitop3:0xde
	v_add_u32_e32 v201, s0, v5
	v_cmp_gt_u32_e32 vcc, 32, v202
	v_lshlrev_b64 v[172:173], 12, v[0:1]
	v_lshlrev_b32_e32 v174, 1, v2
	s_mov_b32 s22, s23
	s_branch .LBB0_105

; __device__ __forceinline__ int v_rd_base(int lane) { return ((lane & 3) << 3) | (((lane >> 2) & 3) << 6) | (((lane >> 4) & 1) << 5) | (((lane >> 5) & 1) << 8); }
; #define NAM(P0, P1, t) do { if constexpr (NA) na_mask(P0, P1, kr_lo + (t), r0, qrow, qc, c0, hi, bl); } while (0)
; #define PSM(P0, P1, MN, AL) do { if constexpr (NA) partialSM(P0, P1, m_reg, MN, AL); else { AL = 1.f; _Pragma("unroll") for (int r = 0; r < 16; ++r) P0[r] = __builtin_amdgcn_exp2f(P0[r]); } } while (0)
; #define VM0() asm volatile("s_waitcnt vmcnt(0)" ::: "memory")
; #define NAM(P0, P1, t) do { if constexpr (NA) na_mask(P0, P1, kr_lo + (t), r0, qrow, qc, c0, hi, bl); } while (0)
; template <bool NA, int ROWB>
; __device__ __forceinline__ void attn_dma(const bf16* __restrict__ Qb, const bf16* __restrict__ Kh, const bf16* __restrict__ Vh, bf16* __restrict__ Ob, int NT, char* lds, const int tid, float* __restrict__ ssb, int qrow0, int kr_lo, const float* bl) {
;     ...
;   float m_reg = -1e30f, l_reg = 0; f32x16 o[4] = {}; bf16x8 qr[8];
;   const int qrow = qrow0 + (wid >> 1), qc = 32 * (wid & 1) + r32;
;   const int c0 = min(max(qc - 8, 0), 48), r0 = min(max(qrow - 4, 0), 120);
;   const bf16* Qw = Qb + (long)(wid * QBLK + r32) * LDQ + hi * 8;
; #pragma unroll
;   for (int d0 = 0; d0 < 8; ++d0) qr[d0] = *reinterpret_cast<const bf16x8*>(Qw + d0 * 16);
;   const int vb0 = (int)(uintptr_t)V_lds + v_rd_base(lane);
;   auto src_off = [&](int i, unsigned& ko, unsigned& vo) __attribute__((always_inline)) {
;     const int b = (wid * 2 + i) * 1024 + lane * 16;
;     { const int row = b >> 8, cb = (b & 255) ^ ((row & 7) << 4); ko = (unsigned)(row * ROWB + cb); }
;     { const int st = b >> 9, within = b & 511, kk = (st >> 2) * 8 + (within >> 6), c = (st & 3) * 32 + ((within & 63) >> 1);
;       const int k = (kk & ~0xC) | ((kk & 4) << 1) | ((kk & 8) >> 1); vo = (unsigned)(k * ROWB + c * 2); }
;   };
;   unsigned ksrc[2], vsrc[2];
;   if constexpr (!NA) { src_off(0, ksrc[0], vsrc[0]); src_off(1, ksrc[1], vsrc[1]); }
;     ...
;   f32x16 pA0, pA1, pB0, pB1; bf16x8 pa0, pa1, pa2, pa3; float mnA, mnB, alA, alB;
;   DMA_TILE(0, 0); DMA_TILE(1, 1); VM0(); __syncthreads();
;   qkt<false>(pA0, pA1, (const bf16*)K_lds, qr, nullptr, r32, hi); NAM(pA0, pA1, 0); PSM(pA0, pA1, mnA, alA);
.LBB0_105:
	s_lshl_b32 s0, s22, 19
	s_and_b32 s0, s0, 0x200000
	v_readlane_b32 s4, v254, 32
	v_readlane_b32 s5, v254, 33
	s_add_u32 s18, s4, s0
	s_addc_u32 s19, s5, 0
	s_lshl_b32 s0, s23, 5
	s_and_b32 s6, s0, 0xffffff00
	s_and_b32 s14, s23, 7
	s_ashr_i32 s7, s6, 31
	s_mul_i32 s1, s6, 0x2400
	s_mul_hi_i32 s0, s6, 0x2400
	s_add_u32 s1, s16, s1
	s_addc_u32 s4, s17, s0
	s_lshl_b32 s15, s14, 7
	s_lshl_b32 s0, s14, 8
	s_add_u32 s0, s1, s0
	s_addc_u32 s1, s4, 0
	s_waitcnt lgkmcnt(0)
	v_lshl_add_u64 v[0:1], s[0:1], 0, v[162:163]
	v_mov_b32_e32 v175, v113
	v_lshl_add_u64 v[0:1], v[0:1], 0, v[174:175]
	s_movk_i32 s0, 0x1000
	v_add_co_u32_e64 v2, s[4:5], s0, v0
	s_nop 1
	v_addc_co_u32_e64 v3, s[4:5], 0, v1, s[4:5]
	s_barrier
	global_load_dwordx4 v[138:141], v[2:3], off offset:2048
	s_mov_b64 s[4:5], 0x1800
	v_lshl_add_u64 v[0:1], v[0:1], 0, s[4:5]
	global_load_dwordx4 v[142:145], v[0:1], off offset:32
	global_load_dwordx4 v[134:137], v[0:1], off offset:64
	global_load_dwordx4 v[114:117], v[0:1], off offset:96
	global_load_dwordx4 v[118:121], v[0:1], off offset:128
	global_load_dwordx4 v[122:125], v[0:1], off offset:160
	global_load_dwordx4 v[126:129], v[0:1], off offset:192
	global_load_dwordx4 v[130:133], v[0:1], off offset:224
	s_lshl_b32 s0, s23, 19
	s_and_b32 s16, s0, 0x200000
	s_add_u32 s0, s12, s16
	s_addc_u32 s1, s13, 0
	s_add_u32 s16, s8, s16
	v_readfirstlane_b32 s4, v184
	s_addc_u32 s17, s9, 0
	s_lshr_b32 s98, s23, 3
	s_lshl_b32 s98, s98, 16
	s_add_u32 s0, s0, s98
	s_addc_u32 s1, s1, 0
	s_add_u32 s16, s16, s98
	s_addc_u32 s17, s17, 0
	s_lshl_b32 s4, s4, 11
	s_add_i32 s5, s4, 0
	v_lshl_add_u64 v[0:1], s[0:1], 0, v[164:165]
	s_add_i32 m0, s5, 0xc000
	v_add_u32_e32 v4, 0, v187
	global_load_lds_dwordx4 v[0:1], off
	v_lshl_add_u64 v[0:1], s[16:17], 0, v[166:167]
	s_mov_b32 m0, s5
	v_add_u32_e32 v8, 0, v188
	global_load_lds_dwordx4 v[0:1], off
	v_lshl_add_u64 v[0:1], s[0:1], 0, v[168:169]
	s_add_i32 m0, s5, 0xc400
	v_add_u32_e32 v12, 0, v194
	global_load_lds_dwordx4 v[0:1], off
	s_add_i32 m0, s5, 0x400
	s_add_u32 s0, s0, 0x4000
	s_addc_u32 s1, s1, 0
	v_lshl_add_u64 v[0:1], s[16:17], 0, v[170:171]
	s_add_u32 s16, s16, 0x4000
	global_load_lds_dwordx4 v[0:1], off
	s_addc_u32 s17, s17, 0
	v_lshl_add_u64 v[0:1], s[0:1], 0, v[164:165]
	s_add_i32 m0, s5, 0x10000
	v_mov_b32_e32 v112, 0
	global_load_lds_dwordx4 v[0:1], off
	v_lshl_add_u64 v[0:1], s[16:17], 0, v[166:167]
	s_add_i32 m0, s5, 0x4000
	s_mov_b32 s38, s36
	global_load_lds_dwordx4 v[0:1], off
	v_lshl_add_u64 v[0:1], s[0:1], 0, v[168:169]
	s_add_i32 m0, s5, 0x10400
	s_mov_b32 s0, 1
	global_load_lds_dwordx4 v[0:1], off
	v_lshl_add_u64 v[0:1], s[16:17], 0, v[170:171]
	s_add_i32 m0, s5, 0x4400
	s_mov_b32 s24, 0
	global_load_lds_dwordx4 v[0:1], off
	s_waitcnt vmcnt(0)
	s_waitcnt vmcnt(0) lgkmcnt(0)
	s_barrier
	ds_read_b128 v[0:3], v4 offset:49152
	ds_read_b128 v[4:7], v4 offset:57344
	s_mov_b32 s17, 2
	s_mov_b32 s16, -1
	v_mov_b32_e32 v13, v112
	s_waitcnt lgkmcnt(1)
	v_mfma_f32_32x32x16_bf16 v[14:29], v[0:3], v[138:141], 0
	v_mov_b32_e32 v34, v112
	v_mov_b32_e32 v35, v112
	v_mov_b32_e32 v36, v112
	v_mov_b32_e32 v37, v112
	v_mov_b32_e32 v38, v112
	v_mov_b32_e32 v39, v112
	v_mov_b32_e32 v40, v112
	s_waitcnt lgkmcnt(0)
	v_mfma_f32_32x32x16_bf16 v[64:79], v[4:7], v[138:141], 0
	ds_read_b128 v[0:3], v8 offset:49152
	ds_read_b128 v[4:7], v8 offset:57344
	v_add_u32_e32 v8, 0, v189
	v_mov_b32_e32 v41, v112
	v_mov_b32_e32 v42, v112
	v_mov_b32_e32 v43, v112
	v_mov_b32_e32 v44, v112
	v_mov_b32_e32 v45, v112
	s_waitcnt lgkmcnt(1)
	v_mfma_f32_32x32x16_bf16 v[14:29], v[0:3], v[142:145], v[14:29]
	v_mov_b32_e32 v46, v112
	v_mov_b32_e32 v47, v112
	v_mov_b32_e32 v48, 0
	v_mov_b32_e32 v49, v112
	v_mov_b32_e32 v50, v112
	v_mov_b32_e32 v51, v112
	v_mov_b32_e32 v52, v112
	s_waitcnt lgkmcnt(0)
	v_mfma_f32_32x32x16_bf16 v[64:79], v[4:7], v[142:145], v[64:79]
	ds_read_b128 v[0:3], v8 offset:49152
	ds_read_b128 v[4:7], v8 offset:57344
	v_add_u32_e32 v8, 0, v190
	v_mov_b32_e32 v53, v112
	v_mov_b32_e32 v54, v112
	v_mov_b32_e32 v55, v112
	v_mov_b32_e32 v56, v112
	v_mov_b32_e32 v57, v112
	s_waitcnt lgkmcnt(1)
	v_mfma_f32_32x32x16_bf16 v[14:29], v[0:3], v[134:137], v[14:29]
	v_mov_b32_e32 v58, v112
	v_mov_b32_e32 v59, v112
	v_mov_b32_e32 v60, v112
	v_mov_b32_e32 v61, v112
	v_mov_b32_e32 v62, v112
	v_mov_b32_e32 v63, v112
	s_mov_b64 s[28:29], 0x25d48000
	s_waitcnt lgkmcnt(0)
	v_mfma_f32_32x32x16_bf16 v[64:79], v[4:7], v[134:137], v[64:79]
	ds_read_b128 v[0:3], v8 offset:49152
	ds_read_b128 v[4:7], v8 offset:57344
	v_add_u32_e32 v8, 0, v191
	s_mov_b64 s[36:37], 0x26148000
	s_mov_b64 s[40:41], 0x25d4c000
	s_mov_b64 s[42:43], 0x2614c000
	s_waitcnt lgkmcnt(1)
	v_mfma_f32_32x32x16_bf16 v[14:29], v[0:3], v[114:117], v[14:29]
	s_waitcnt lgkmcnt(0)
	v_mfma_f32_32x32x16_bf16 v[64:79], v[4:7], v[114:117], v[64:79]
	ds_read_b128 v[0:3], v8 offset:49152
	ds_read_b128 v[4:7], v8 offset:57344
	v_add_u32_e32 v8, 0, v192
	s_waitcnt lgkmcnt(1)
	v_mfma_f32_32x32x16_bf16 v[14:29], v[0:3], v[118:121], v[14:29]
	s_waitcnt lgkmcnt(0)
	v_mfma_f32_32x32x16_bf16 v[64:79], v[4:7], v[118:121], v[64:79]
	ds_read_b128 v[0:3], v8 offset:49152
	ds_read_b128 v[4:7], v8 offset:57344
	v_add_u32_e32 v8, 0, v193
	s_waitcnt lgkmcnt(1)
	v_mfma_f32_32x32x16_bf16 v[14:29], v[0:3], v[122:125], v[14:29]
	s_waitcnt lgkmcnt(0)
	v_mfma_f32_32x32x16_bf16 v[64:79], v[4:7], v[122:125], v[64:79]
	ds_read_b128 v[0:3], v8 offset:49152
	ds_read_b128 v[4:7], v8 offset:57344
	ds_read_b128 v[8:11], v12 offset:49152
	ds_read_b128 v[30:33], v12 offset:57344
	v_mov_b32_e32 v12, v112
	s_waitcnt lgkmcnt(3)
; #define SBAR() __builtin_amdgcn_sched_barrier(0)
; #define NAM(P0, P1, t) do { if constexpr (NA) na_mask(P0, P1, kr_lo + (t), r0, qrow, qc, c0, hi, bl); } while (0)
; #define PSM(P0, P1, MN, AL) do { if constexpr (NA) partialSM(P0, P1, m_reg, MN, AL); else { AL = 1.f; _Pragma("unroll") for (int r = 0; r < 16; ++r) P0[r] = __builtin_amdgcn_exp2f(P0[r]); } } while (0)
; #define RESCN(a) do { if constexpr (NA) RESC(a); } while (0)
; #define VM0() asm volatile("s_waitcnt vmcnt(0)" ::: "memory")
; #define NAM(P0, P1, t) do { if constexpr (NA) na_mask(P0, P1, kr_lo + (t), r0, qrow, qc, c0, hi, bl); } while (0)
; #define PSM(P0, P1, MN, AL) do { if constexpr (NA) partialSM(P0, P1, m_reg, MN, AL); else { AL = 1.f; _Pragma("unroll") for (int r = 0; r < 16; ++r) P0[r] = __builtin_amdgcn_exp2f(P0[r]); } } while (0)
; #define RESCN(a) do { if constexpr (NA) RESC(a); } while (0)
; template <bool NA, int ROWB>
; __device__ __forceinline__ void attn_dma(const bf16* __restrict__ Qb, const bf16* __restrict__ Kh, const bf16* __restrict__ Vh, bf16* __restrict__ Ob, int NT, char* lds, const int tid, float* __restrict__ ssb, int qrow0, int kr_lo, const float* bl) {
;     ...
;   DMA_TILE(0, 0); DMA_TILE(1, 1); VM0(); __syncthreads();
;   qkt<false>(pA0, pA1, (const bf16*)K_lds, qr, nullptr, r32, hi); NAM(pA0, pA1, 0); PSM(pA0, pA1, mnA, alA);
;   int bp = 0, bc = 1, bn = 2;
;   for (int t = 1; t + 1 < NT; t += 2) {
;     DMA_TILE(t + 1, bn);
;     SBAR(); qkt<false>(pB0, pB1, (const bf16*)(K_lds + bc * SHM_K), qr, nullptr, r32, hi); NAM(pB0, pB1, t);
;     finishSM(pA0, pA1, alA, l_reg, pa0, pa1, pa2, pa3); SBAR();
;     pv_d0(o, vb0 + bp * (int)SHM_V, pa0, pa1, pa2, pa3); PSM(pB0, pB1, mnB, alB); RESCN(alB);
;     VM0(); __syncthreads();
;     bp = bc; bc = bn; bn = NEXTB(bn);
;     if (t + 2 < NT) DMA_TILE(t + 2, bn);
;     SBAR(); qkt<false>(pA0, pA1, (const bf16*)(K_lds + bc * SHM_K), qr, nullptr, r32, hi); NAM(pA0, pA1, t + 1);
;     finishSM(pB0, pB1, alB, l_reg, pa0, pa1, pa2, pa3); SBAR();
;     pv_d0(o, vb0 + bp * (int)SHM_V, pa0, pa1, pa2, pa3); PSM(pA0, pA1, mnA, alA); RESCN(alA);
	v_mfma_f32_32x32x16_bf16 v[14:29], v[0:3], v[126:129], v[14:29]
	v_mov_b32_e32 v0, 0
	v_mov_b32_e32 v1, v112
	v_mov_b32_e32 v2, v112
	v_mov_b32_e32 v3, v112
	s_waitcnt lgkmcnt(2)
	v_mfma_f32_32x32x16_bf16 v[64:79], v[4:7], v[126:129], v[64:79]
	v_mov_b32_e32 v4, v112
	v_mov_b32_e32 v5, v112
	v_mov_b32_e32 v6, v112
	v_mov_b32_e32 v7, v112
	s_waitcnt lgkmcnt(1)
	v_mfma_f32_32x32x16_bf16 v[14:29], v[8:11], v[130:133], v[14:29]
	v_mov_b32_e32 v8, v112
	v_mov_b32_e32 v9, v112
	v_mov_b32_e32 v10, v112
	v_mov_b32_e32 v11, v112
	s_waitcnt lgkmcnt(0)
	v_mfma_f32_32x32x16_bf16 v[64:79], v[30:33], v[130:133], v[64:79]
	s_nop 5
	v_exp_f32_e32 v212, v14
	v_exp_f32_e32 v214, v15
	v_exp_f32_e32 v210, v16
	v_exp_f32_e32 v213, v17
	v_exp_f32_e32 v208, v18
	v_exp_f32_e32 v211, v19
	v_exp_f32_e32 v207, v20
	v_exp_f32_e32 v209, v21
	v_exp_f32_e32 v203, v22
	v_exp_f32_e32 v206, v23
	v_exp_f32_e32 v198, v24
	v_exp_f32_e32 v205, v25
	v_exp_f32_e32 v196, v26
	v_exp_f32_e32 v199, v27
	v_exp_f32_e32 v175, v28
	v_exp_f32_e32 v197, v29
	v_mov_b32_e32 v14, v112
	v_mov_b32_e32 v15, v112
	v_mov_b32_e32 v16, 0
	v_mov_b32_e32 v17, v112
	v_mov_b32_e32 v18, v112
	v_mov_b32_e32 v19, v112
	v_mov_b32_e32 v20, v112
	v_mov_b32_e32 v21, v112
	v_mov_b32_e32 v22, v112
	v_mov_b32_e32 v23, v112
	v_mov_b32_e32 v24, v112
	v_mov_b32_e32 v25, v112
	v_mov_b32_e32 v26, v112
	v_mov_b32_e32 v27, v112
	v_mov_b32_e32 v28, v112
	v_mov_b32_e32 v29, v112
	v_mov_b32_e32 v30, v112
	v_mov_b32_e32 v31, v112
	v_mov_b32_e32 v32, 0
	v_mov_b32_e32 v33, v112
	v_exp_f32_e32 v64, v64
	v_exp_f32_e32 v65, v65
	v_exp_f32_e32 v66, v66
	v_exp_f32_e32 v67, v67
	v_exp_f32_e32 v68, v68
	v_exp_f32_e32 v69, v69
	v_exp_f32_e32 v70, v70
	v_exp_f32_e32 v71, v71
	v_exp_f32_e32 v72, v72
	v_exp_f32_e32 v73, v73
	v_exp_f32_e32 v74, v74
	v_exp_f32_e32 v75, v75
	v_exp_f32_e32 v76, v76
	v_exp_f32_e32 v77, v77
	v_exp_f32_e32 v78, v78
	v_exp_f32_e32 v79, v79
	s_mov_b32 s24, 0
	s_mov_b32 s0, 0x4000
	s_mov_b32 s17, 0x8000
	s_add_u32 s40, s18, s28
	s_addc_u32 s41, s19, s29
	s_sub_u32 s40, s40, 0x8000
	s_subb_u32 s41, s41, 0
	s_add_u32 s42, s18, s36
	s_addc_u32 s43, s19, s37
	s_sub_u32 s42, s42, 0x8000
	s_subb_u32 s43, s43, 0
	s_add_u32 s18, s98, 0x8000
	s_barrier
	s_add_u32 s98, s40, s18
	s_addc_u32 s99, s41, 0
	s_add_i32 s25, s17, s4
	s_add_i32 m0, s25, 0xc000
	s_nop 0
	global_load_lds_dwordx4 v164, s[98:99]
	s_add_i32 m0, s25, 0xc400
	s_nop 0
	global_load_lds_dwordx4 v168, s[98:99]
	s_add_u32 s100, s42, s18
	s_addc_u32 s101, s43, 0
	s_add_i32 s18, s18, 0x4000
	s_and_b32 s18, s18, 0x1fffff
	s_add_u32 s98, s40, s18
	s_addc_u32 s99, s41, 0
	s_add_i32 s1, s24, s4
	s_add_i32 s25, s17, s4
	v_add_u32_e32 v232, s0, v187
	ds_read_b128 v[176:179], v232 offset:49152
	s_add_i32 m0, s1, 0xc000
	s_nop 0
	global_load_lds_dwordx4 v164, s[98:99]
	ds_read_b128 v[180:183], v232 offset:57344
	v_add_u32_e32 v238, s0, v188
	ds_read_b128 v[240:243], v238 offset:49152
	ds_read_b128 v[244:247], v238 offset:57344
	v_add_u32_e32 v232, s0, v189
	ds_read_b128 v[248:251], v232 offset:49152
	s_branch .Lgqa_a1
.Lgqa_top:
	s_mov_b32 s1, s24
	s_mov_b32 s24, s0
	s_mov_b32 s0, s17
	s_mov_b32 s17, s1
	s_add_u32 s100, s42, s18
	s_addc_u32 s101, s43, 0
	s_add_i32 s18, s18, 0x4000
	s_and_b32 s18, s18, 0x1fffff
	s_add_u32 s98, s40, s18
	s_addc_u32 s99, s41, 0
	s_add_i32 s1, s24, s4
	s_add_i32 s25, s17, s4
	v_add_u32_e32 v232, s0, v187
	ds_read_b128 v[176:179], v232 offset:49152
	ds_read_b128 v[180:183], v232 offset:57344
	s_add_i32 m0, s1, 0xc000
	s_nop 0
	global_load_lds_dwordx4 v164, s[98:99]
	v_mfma_f32_32x32x16_bf16 v[48:63], v[108:111], v[234:237], v[48:63]
	v_add_u32_e32 v238, s0, v188
	ds_read_b128 v[240:243], v238 offset:49152
	v_mfma_f32_32x32x16_bf16 v[48:63], v[96:99], v[146:149], v[48:63]
	ds_read_b128 v[244:247], v238 offset:57344
	v_mfma_f32_32x32x16_bf16 v[48:63], v[100:103], v[150:153], v[48:63]
	v_add_u32_e32 v232, s0, v189
	ds_read_b128 v[248:251], v232 offset:49152
.Lgqa_a1:
	s_waitcnt lgkmcnt(4)
	v_mfma_f32_32x32x16_bf16 v[80:95], v[176:179], v[138:141], 0
	ds_read_b128 v[234:237], v232 offset:57344
	v_add_f32_e32 v112, v212, v112
	v_add_f32_e32 v112, v214, v112
	v_add_f32_e32 v112, v210, v112
	v_add_f32_e32 v112, v213, v112
	s_waitcnt lgkmcnt(4)
	v_mfma_f32_32x32x16_bf16 v[96:111], v[180:183], v[138:141], 0
	v_add_u32_e32 v238, s0, v190
	ds_read_b128 v[146:149], v238 offset:49152
	v_add_f32_e32 v112, v208, v112
	v_add_f32_e32 v112, v211, v112
	v_add_f32_e32 v112, v207, v112
	v_add_f32_e32 v112, v209, v112
	s_waitcnt lgkmcnt(4)
	v_mfma_f32_32x32x16_bf16 v[80:95], v[240:243], v[142:145], v[80:95]
	ds_read_b128 v[150:153], v238 offset:57344
	v_add_f32_e32 v112, v203, v112
	v_add_f32_e32 v112, v206, v112
	v_add_f32_e32 v112, v198, v112
	v_add_f32_e32 v112, v205, v112
	s_waitcnt lgkmcnt(4)
	v_mfma_f32_32x32x16_bf16 v[96:111], v[244:247], v[142:145], v[96:111]
	v_add_u32_e32 v232, s0, v191
	ds_read_b128 v[176:179], v232 offset:49152
	v_add_f32_e32 v112, v196, v112
	v_add_f32_e32 v112, v199, v112
	v_add_f32_e32 v112, v175, v112
	v_add_f32_e32 v112, v197, v112
	s_waitcnt lgkmcnt(4)
	v_mfma_f32_32x32x16_bf16 v[80:95], v[248:251], v[134:137], v[80:95]
	ds_read_b128 v[180:183], v232 offset:57344
	v_add_f32_e32 v112, v64, v112
	v_add_f32_e32 v112, v65, v112
	v_add_f32_e32 v112, v66, v112
	v_add_f32_e32 v112, v67, v112
	s_waitcnt lgkmcnt(4)
	v_mfma_f32_32x32x16_bf16 v[96:111], v[234:237], v[134:137], v[96:111]
	v_add_u32_e32 v238, s0, v192
	ds_read_b128 v[240:243], v238 offset:49152
	v_add_f32_e32 v112, v68, v112
	v_add_f32_e32 v112, v69, v112
	v_add_f32_e32 v112, v70, v112
	v_add_f32_e32 v112, v71, v112
	s_mov_b32 m0, s25
	s_nop 0
	global_load_lds_dwordx4 v166, s[100:101]
	s_waitcnt lgkmcnt(4)
; #define SBAR() __builtin_amdgcn_sched_barrier(0)
; #define NAM(P0, P1, t) do { if constexpr (NA) na_mask(P0, P1, kr_lo + (t), r0, qrow, qc, c0, hi, bl); } while (0)
; #define PSM(P0, P1, MN, AL) do { if constexpr (NA) partialSM(P0, P1, m_reg, MN, AL); else { AL = 1.f; _Pragma("unroll") for (int r = 0; r < 16; ++r) P0[r] = __builtin_amdgcn_exp2f(P0[r]); } } while (0)
; #define RESCN(a) do { if constexpr (NA) RESC(a); } while (0)
; #define VM0() asm volatile("s_waitcnt vmcnt(0)" ::: "memory")
; #define NAM(P0, P1, t) do { if constexpr (NA) na_mask(P0, P1, kr_lo + (t), r0, qrow, qc, c0, hi, bl); } while (0)
; #define RESCN(a) do { if constexpr (NA) RESC(a); } while (0)
; __device__ __forceinline__ void finishSM(f32x16& p0, f32x16& p1, float alpha, float& l_reg, bf16x8& pa0, bf16x8& pa1, bf16x8& pa2, bf16x8& pa3) {
;   for (int r = 0; r < 16; ++r) p1[r] = __builtin_amdgcn_exp2f(p1[r]);
;   float ps = 0; for (int r = 0; r < 16; ++r) ps += p0[r]; for (int r = 0; r < 16; ++r) ps += p1[r];
;   { auto rr = __builtin_amdgcn_permlane32_swap(__float_as_uint(ps), __float_as_uint(ps), false, false);
;     ps = __uint_as_float(rr[0]) + __uint_as_float(rr[1]); }
;   l_reg = l_reg * alpha + ps;
;     ...
;   PK4(p0, 0, pa0); PK4(p0, 8, pa1); PK4(p1, 0, pa2); PK4(p1, 8, pa3);
; template <bool NA, int ROWB>
; __device__ __forceinline__ void attn_dma(const bf16* __restrict__ Qb, const bf16* __restrict__ Kh, const bf16* __restrict__ Vh, bf16* __restrict__ Ob, int NT, char* lds, const int tid, float* __restrict__ ssb, int qrow0, int kr_lo, const float* bl) {
;     ...
;   for (int t = 1; t + 1 < NT; t += 2) {
;     DMA_TILE(t + 1, bn);
;     SBAR(); qkt<false>(pB0, pB1, (const bf16*)(K_lds + bc * SHM_K), qr, nullptr, r32, hi); NAM(pB0, pB1, t);
;     finishSM(pA0, pA1, alA, l_reg, pa0, pa1, pa2, pa3); SBAR();
;     pv_d0(o, vb0 + bp * (int)SHM_V, pa0, pa1, pa2, pa3); PSM(pB0, pB1, mnB, alB); RESCN(alB);
;     VM0(); __syncthreads();
;     bp = bc; bc = bn; bn = NEXTB(bn);
;     if (t + 2 < NT) DMA_TILE(t + 2, bn);
;     SBAR(); qkt<false>(pA0, pA1, (const bf16*)(K_lds + bc * SHM_K), qr, nullptr, r32, hi); NAM(pA0, pA1, t + 1);
;     finishSM(pB0, pB1, alB, l_reg, pa0, pa1, pa2, pa3); SBAR();
;     pv_d0(o, vb0 + bp * (int)SHM_V, pa0, pa1, pa2, pa3); PSM(pA0, pA1, mnA, alA); RESCN(alA);
;     VM0(); __syncthreads();
	v_mfma_f32_32x32x16_bf16 v[80:95], v[146:149], v[114:117], v[80:95]
	ds_read_b128 v[244:247], v238 offset:57344
	v_add_f32_e32 v112, v72, v112
	v_add_f32_e32 v112, v73, v112
	v_add_f32_e32 v112, v74, v112
	v_add_f32_e32 v112, v75, v112
	s_waitcnt lgkmcnt(4)
	v_mfma_f32_32x32x16_bf16 v[96:111], v[150:153], v[114:117], v[96:111]
	v_add_u32_e32 v232, s0, v193
	ds_read_b128 v[248:251], v232 offset:49152
	v_add_f32_e32 v112, v76, v112
	v_add_f32_e32 v112, v77, v112
	v_add_f32_e32 v112, v78, v112
	v_add_f32_e32 v112, v79, v112
	s_waitcnt lgkmcnt(4)
	v_mfma_f32_32x32x16_bf16 v[80:95], v[176:179], v[118:121], v[80:95]
	ds_read_b128 v[234:237], v232 offset:57344
	v_cvt_pk_bf16_f32 v64, v64, v65
	v_cvt_pk_bf16_f32 v65, v66, v67
	v_cvt_pk_bf16_f32 v66, v68, v69
	v_cvt_pk_bf16_f32 v67, v70, v71
	s_waitcnt lgkmcnt(4)
	v_mfma_f32_32x32x16_bf16 v[96:111], v[180:183], v[118:121], v[96:111]
	v_add_u32_e32 v238, s0, v194
	ds_read_b128 v[146:149], v238 offset:49152
	v_cvt_pk_bf16_f32 v68, v72, v73
	v_cvt_pk_bf16_f32 v69, v74, v75
	v_cvt_pk_bf16_f32 v70, v76, v77
	v_cvt_pk_bf16_f32 v71, v78, v79
	s_waitcnt lgkmcnt(4)
	v_mfma_f32_32x32x16_bf16 v[80:95], v[240:243], v[122:125], v[80:95]
	ds_read_b128 v[150:153], v238 offset:57344
	v_cvt_pk_bf16_f32 v72, v212, v214
	v_cvt_pk_bf16_f32 v73, v210, v213
	v_cvt_pk_bf16_f32 v74, v208, v211
	v_cvt_pk_bf16_f32 v75, v207, v209
	s_waitcnt lgkmcnt(4)
	v_mfma_f32_32x32x16_bf16 v[96:111], v[244:247], v[122:125], v[96:111]
	v_add_u32_e32 v154, s24, v195
	ds_read_b64_tr_b16 v[176:177], v154 offset:0
	ds_read_b64_tr_b16 v[178:179], v154 offset:2048
	v_cvt_pk_bf16_f32 v76, v203, v206
	v_cvt_pk_bf16_f32 v77, v198, v205
	v_cvt_pk_bf16_f32 v78, v196, v199
	v_cvt_pk_bf16_f32 v79, v175, v197
	s_waitcnt lgkmcnt(5)
	v_mfma_f32_32x32x16_bf16 v[80:95], v[248:251], v[126:129], v[80:95]
	ds_read_b64_tr_b16 v[180:181], v154 offset:4096
	ds_read_b64_tr_b16 v[182:183], v154 offset:6144
	s_waitcnt lgkmcnt(6)
	v_mfma_f32_32x32x16_bf16 v[96:111], v[234:237], v[126:129], v[96:111]
	ds_read_b64_tr_b16 v[240:241], v154 offset:8192
	ds_read_b64_tr_b16 v[242:243], v154 offset:10240
	s_add_i32 m0, s1, 0xc400
	s_nop 0
	global_load_lds_dwordx4 v168, s[98:99]
	s_waitcnt lgkmcnt(7)
	v_mfma_f32_32x32x16_bf16 v[80:95], v[146:149], v[130:133], v[80:95]
	ds_read_b64_tr_b16 v[244:245], v154 offset:12288
	ds_read_b64_tr_b16 v[246:247], v154 offset:14336
	s_waitcnt lgkmcnt(8)
	v_mfma_f32_32x32x16_bf16 v[96:111], v[150:153], v[130:133], v[96:111]
	ds_read_b64_tr_b16 v[248:249], v154 offset:512
	ds_read_b64_tr_b16 v[250:251], v154 offset:2560
	s_waitcnt lgkmcnt(8)
	v_mfma_f32_32x32x16_bf16 v[0:15], v[72:75], v[176:179], v[0:15]
	ds_read_b64_tr_b16 v[234:235], v154 offset:4608
	ds_read_b64_tr_b16 v[236:237], v154 offset:6656
	s_waitcnt lgkmcnt(8)
	v_mfma_f32_32x32x16_bf16 v[0:15], v[76:79], v[180:183], v[0:15]
	ds_read_b64_tr_b16 v[146:147], v154 offset:8704
	ds_read_b64_tr_b16 v[148:149], v154 offset:10752
	v_exp_f32_e32 v215, v80
	v_exp_f32_e32 v216, v81
	v_exp_f32_e32 v217, v82
	s_waitcnt lgkmcnt(8)
	v_mfma_f32_32x32x16_bf16 v[0:15], v[64:67], v[240:243], v[0:15]
	ds_read_b64_tr_b16 v[150:151], v154 offset:12800
	ds_read_b64_tr_b16 v[152:153], v154 offset:14848
	v_exp_f32_e32 v218, v83
	v_exp_f32_e32 v219, v84
	v_exp_f32_e32 v220, v85
	s_waitcnt lgkmcnt(8)
	v_mfma_f32_32x32x16_bf16 v[0:15], v[68:71], v[244:247], v[0:15]
	ds_read_b64_tr_b16 v[176:177], v154 offset:1024
	ds_read_b64_tr_b16 v[178:179], v154 offset:3072
	v_exp_f32_e32 v221, v86
	v_exp_f32_e32 v222, v87
	v_exp_f32_e32 v223, v88
	s_waitcnt lgkmcnt(8)
	v_mfma_f32_32x32x16_bf16 v[16:31], v[72:75], v[248:251], v[16:31]
	ds_read_b64_tr_b16 v[180:181], v154 offset:5120
	ds_read_b64_tr_b16 v[182:183], v154 offset:7168
	v_exp_f32_e32 v224, v89
	v_exp_f32_e32 v225, v90
	v_exp_f32_e32 v226, v91
	s_waitcnt lgkmcnt(8)
	v_mfma_f32_32x32x16_bf16 v[16:31], v[76:79], v[234:237], v[16:31]
	ds_read_b64_tr_b16 v[240:241], v154 offset:9216
	ds_read_b64_tr_b16 v[242:243], v154 offset:11264
	v_exp_f32_e32 v227, v92
	v_exp_f32_e32 v228, v93
	v_exp_f32_e32 v229, v94
	s_add_i32 m0, s25, 0x400
	s_nop 0
	global_load_lds_dwordx4 v170, s[100:101]
	s_waitcnt lgkmcnt(8)
	v_mfma_f32_32x32x16_bf16 v[16:31], v[64:67], v[146:149], v[16:31]
	ds_read_b64_tr_b16 v[244:245], v154 offset:13312
	ds_read_b64_tr_b16 v[246:247], v154 offset:15360
	v_exp_f32_e32 v230, v95
	v_exp_f32_e32 v96, v96
	v_exp_f32_e32 v97, v97
	s_waitcnt lgkmcnt(8)
	v_mfma_f32_32x32x16_bf16 v[16:31], v[68:71], v[150:153], v[16:31]
	ds_read_b64_tr_b16 v[248:249], v154 offset:1536
	ds_read_b64_tr_b16 v[250:251], v154 offset:3584
	v_exp_f32_e32 v98, v98
	v_exp_f32_e32 v99, v99
	v_exp_f32_e32 v100, v100
	s_waitcnt lgkmcnt(8)
	v_mfma_f32_32x32x16_bf16 v[32:47], v[72:75], v[176:179], v[32:47]
	ds_read_b64_tr_b16 v[234:235], v154 offset:5632
	ds_read_b64_tr_b16 v[236:237], v154 offset:7680
	v_exp_f32_e32 v101, v101
	v_exp_f32_e32 v102, v102
	v_exp_f32_e32 v103, v103
	s_waitcnt lgkmcnt(8)
	v_mfma_f32_32x32x16_bf16 v[32:47], v[76:79], v[180:183], v[32:47]
	ds_read_b64_tr_b16 v[146:147], v154 offset:9728
	ds_read_b64_tr_b16 v[148:149], v154 offset:11776
	v_exp_f32_e32 v104, v104
	v_exp_f32_e32 v105, v105
	s_waitcnt lgkmcnt(8)
	v_mfma_f32_32x32x16_bf16 v[32:47], v[64:67], v[240:243], v[32:47]
	ds_read_b64_tr_b16 v[150:151], v154 offset:13824
	ds_read_b64_tr_b16 v[152:153], v154 offset:15872
	v_exp_f32_e32 v106, v106
	v_exp_f32_e32 v107, v107
	s_waitcnt lgkmcnt(8)
	v_mfma_f32_32x32x16_bf16 v[32:47], v[68:71], v[244:247], v[32:47]
	v_exp_f32_e32 v108, v108
	v_exp_f32_e32 v109, v109
	s_waitcnt lgkmcnt(6)
	v_mfma_f32_32x32x16_bf16 v[48:63], v[72:75], v[248:251], v[48:63]
	v_exp_f32_e32 v110, v110
	v_exp_f32_e32 v111, v111
	s_waitcnt vmcnt(4) lgkmcnt(0)
	s_barrier
; #define SBAR() __builtin_amdgcn_sched_barrier(0)
; #define NAM(P0, P1, t) do { if constexpr (NA) na_mask(P0, P1, kr_lo + (t), r0, qrow, qc, c0, hi, bl); } while (0)
; #define PSM(P0, P1, MN, AL) do { if constexpr (NA) partialSM(P0, P1, m_reg, MN, AL); else { AL = 1.f; _Pragma("unroll") for (int r = 0; r < 16; ++r) P0[r] = __builtin_amdgcn_exp2f(P0[r]); } } while (0)
; #define RESCN(a) do { if constexpr (NA) RESC(a); } while (0)
; #define VM0() asm volatile("s_waitcnt vmcnt(0)" ::: "memory")
; #define NAM(P0, P1, t) do { if constexpr (NA) na_mask(P0, P1, kr_lo + (t), r0, qrow, qc, c0, hi, bl); } while (0)
; #define RESCN(a) do { if constexpr (NA) RESC(a); } while (0)
; __device__ __forceinline__ void finishSM(f32x16& p0, f32x16& p1, float alpha, float& l_reg, bf16x8& pa0, bf16x8& pa1, bf16x8& pa2, bf16x8& pa3) {
;   for (int r = 0; r < 16; ++r) p1[r] = __builtin_amdgcn_exp2f(p1[r]);
;   float ps = 0; for (int r = 0; r < 16; ++r) ps += p0[r]; for (int r = 0; r < 16; ++r) ps += p1[r];
;   { auto rr = __builtin_amdgcn_permlane32_swap(__float_as_uint(ps), __float_as_uint(ps), false, false);
;     ps = __uint_as_float(rr[0]) + __uint_as_float(rr[1]); }
;   l_reg = l_reg * alpha + ps;
;     ...
;   PK4(p0, 0, pa0); PK4(p0, 8, pa1); PK4(p1, 0, pa2); PK4(p1, 8, pa3);
; template <bool NA, int ROWB>
; __device__ __forceinline__ void attn_dma(const bf16* __restrict__ Qb, const bf16* __restrict__ Kh, const bf16* __restrict__ Vh, bf16* __restrict__ Ob, int NT, char* lds, const int tid, float* __restrict__ ssb, int qrow0, int kr_lo, const float* bl) {
;     ...
;   for (int t = 1; t + 1 < NT; t += 2) {
;     DMA_TILE(t + 1, bn);
;     SBAR(); qkt<false>(pB0, pB1, (const bf16*)(K_lds + bc * SHM_K), qr, nullptr, r32, hi); NAM(pB0, pB1, t);
;     finishSM(pA0, pA1, alA, l_reg, pa0, pa1, pa2, pa3); SBAR();
;     pv_d0(o, vb0 + bp * (int)SHM_V, pa0, pa1, pa2, pa3); PSM(pB0, pB1, mnB, alB); RESCN(alB);
;     VM0(); __syncthreads();
;     bp = bc; bc = bn; bn = NEXTB(bn);
;     if (t + 2 < NT) DMA_TILE(t + 2, bn);
;     SBAR(); qkt<false>(pA0, pA1, (const bf16*)(K_lds + bc * SHM_K), qr, nullptr, r32, hi); NAM(pA0, pA1, t + 1);
;     finishSM(pB0, pB1, alB, l_reg, pa0, pa1, pa2, pa3); SBAR();
;     pv_d0(o, vb0 + bp * (int)SHM_V, pa0, pa1, pa2, pa3); PSM(pA0, pA1, mnA, alA); RESCN(alA);
;     VM0(); __syncthreads();
	s_mov_b32 s1, s24
	s_mov_b32 s24, s0
	s_mov_b32 s0, s17
	s_mov_b32 s17, s1
	s_add_u32 s100, s42, s18
	s_addc_u32 s101, s43, 0
	s_add_i32 s18, s18, 0x4000
	s_and_b32 s18, s18, 0x1fffff
	s_add_u32 s98, s40, s18
	s_addc_u32 s99, s41, 0
	s_add_i32 s1, s24, s4
	s_add_i32 s25, s17, s4
	v_add_u32_e32 v232, s0, v187
	ds_read_b128 v[176:179], v232 offset:49152
	ds_read_b128 v[180:183], v232 offset:57344
	s_add_i32 m0, s1, 0xc000
	s_nop 0
	global_load_lds_dwordx4 v164, s[98:99]
	v_mfma_f32_32x32x16_bf16 v[48:63], v[76:79], v[234:237], v[48:63]
	v_add_u32_e32 v238, s0, v188
	ds_read_b128 v[240:243], v238 offset:49152
	v_mfma_f32_32x32x16_bf16 v[48:63], v[64:67], v[146:149], v[48:63]
	ds_read_b128 v[244:247], v238 offset:57344
	v_mfma_f32_32x32x16_bf16 v[48:63], v[68:71], v[150:153], v[48:63]
	v_add_u32_e32 v232, s0, v189
	ds_read_b128 v[248:251], v232 offset:49152
	s_waitcnt lgkmcnt(4)
	v_mfma_f32_32x32x16_bf16 v[80:95], v[176:179], v[138:141], 0
	ds_read_b128 v[234:237], v232 offset:57344
	v_add_f32_e32 v112, v215, v112
	v_add_f32_e32 v112, v216, v112
	v_add_f32_e32 v112, v217, v112
	v_add_f32_e32 v112, v218, v112
	s_waitcnt lgkmcnt(4)
	v_mfma_f32_32x32x16_bf16 v[64:79], v[180:183], v[138:141], 0
	v_add_u32_e32 v238, s0, v190
	ds_read_b128 v[146:149], v238 offset:49152
	v_add_f32_e32 v112, v219, v112
	v_add_f32_e32 v112, v220, v112
	v_add_f32_e32 v112, v221, v112
	v_add_f32_e32 v112, v222, v112
	s_waitcnt lgkmcnt(4)
	v_mfma_f32_32x32x16_bf16 v[80:95], v[240:243], v[142:145], v[80:95]
	ds_read_b128 v[150:153], v238 offset:57344
	v_add_f32_e32 v112, v223, v112
	v_add_f32_e32 v112, v224, v112
	v_add_f32_e32 v112, v225, v112
	v_add_f32_e32 v112, v226, v112
	s_waitcnt lgkmcnt(4)
	v_mfma_f32_32x32x16_bf16 v[64:79], v[244:247], v[142:145], v[64:79]
	v_add_u32_e32 v232, s0, v191
	ds_read_b128 v[176:179], v232 offset:49152
	v_add_f32_e32 v112, v227, v112
	v_add_f32_e32 v112, v228, v112
	v_add_f32_e32 v112, v229, v112
	v_add_f32_e32 v112, v230, v112
	s_waitcnt lgkmcnt(4)
	v_mfma_f32_32x32x16_bf16 v[80:95], v[248:251], v[134:137], v[80:95]
	ds_read_b128 v[180:183], v232 offset:57344
	v_add_f32_e32 v112, v96, v112
	v_add_f32_e32 v112, v97, v112
	v_add_f32_e32 v112, v98, v112
	v_add_f32_e32 v112, v99, v112
	s_waitcnt lgkmcnt(4)
	v_mfma_f32_32x32x16_bf16 v[64:79], v[234:237], v[134:137], v[64:79]
	v_add_u32_e32 v238, s0, v192
	ds_read_b128 v[240:243], v238 offset:49152
	v_add_f32_e32 v112, v100, v112
	v_add_f32_e32 v112, v101, v112
	v_add_f32_e32 v112, v102, v112
	v_add_f32_e32 v112, v103, v112
	s_mov_b32 m0, s25
	s_nop 0
	global_load_lds_dwordx4 v166, s[100:101]
	s_waitcnt lgkmcnt(4)
	v_mfma_f32_32x32x16_bf16 v[80:95], v[146:149], v[114:117], v[80:95]
	ds_read_b128 v[244:247], v238 offset:57344
	v_add_f32_e32 v112, v104, v112
	v_add_f32_e32 v112, v105, v112
	v_add_f32_e32 v112, v106, v112
	v_add_f32_e32 v112, v107, v112
	s_waitcnt lgkmcnt(4)
	v_mfma_f32_32x32x16_bf16 v[64:79], v[150:153], v[114:117], v[64:79]
	v_add_u32_e32 v232, s0, v193
	ds_read_b128 v[248:251], v232 offset:49152
	v_add_f32_e32 v112, v108, v112
	v_add_f32_e32 v112, v109, v112
	v_add_f32_e32 v112, v110, v112
	v_add_f32_e32 v112, v111, v112
	s_waitcnt lgkmcnt(4)
	v_mfma_f32_32x32x16_bf16 v[80:95], v[176:179], v[118:121], v[80:95]
	ds_read_b128 v[234:237], v232 offset:57344
	v_cvt_pk_bf16_f32 v96, v96, v97
	v_cvt_pk_bf16_f32 v97, v98, v99
	v_cvt_pk_bf16_f32 v98, v100, v101
	v_cvt_pk_bf16_f32 v99, v102, v103
	s_waitcnt lgkmcnt(4)
	v_mfma_f32_32x32x16_bf16 v[64:79], v[180:183], v[118:121], v[64:79]
	v_add_u32_e32 v238, s0, v194
	ds_read_b128 v[146:149], v238 offset:49152
	v_cvt_pk_bf16_f32 v100, v104, v105
	v_cvt_pk_bf16_f32 v101, v106, v107
	v_cvt_pk_bf16_f32 v102, v108, v109
	v_cvt_pk_bf16_f32 v103, v110, v111
	s_waitcnt lgkmcnt(4)
	v_mfma_f32_32x32x16_bf16 v[80:95], v[240:243], v[122:125], v[80:95]
	ds_read_b128 v[150:153], v238 offset:57344
	v_cvt_pk_bf16_f32 v104, v215, v216
	v_cvt_pk_bf16_f32 v105, v217, v218
	v_cvt_pk_bf16_f32 v106, v219, v220
	v_cvt_pk_bf16_f32 v107, v221, v222
	s_waitcnt lgkmcnt(4)
	v_mfma_f32_32x32x16_bf16 v[64:79], v[244:247], v[122:125], v[64:79]
	v_add_u32_e32 v154, s24, v195
	ds_read_b64_tr_b16 v[176:177], v154 offset:0
	ds_read_b64_tr_b16 v[178:179], v154 offset:2048
	v_cvt_pk_bf16_f32 v108, v223, v224
	v_cvt_pk_bf16_f32 v109, v225, v226
	v_cvt_pk_bf16_f32 v110, v227, v228
	v_cvt_pk_bf16_f32 v111, v229, v230
	s_waitcnt lgkmcnt(5)
	v_mfma_f32_32x32x16_bf16 v[80:95], v[248:251], v[126:129], v[80:95]
	ds_read_b64_tr_b16 v[180:181], v154 offset:4096
	ds_read_b64_tr_b16 v[182:183], v154 offset:6144
	s_waitcnt lgkmcnt(6)
	v_mfma_f32_32x32x16_bf16 v[64:79], v[234:237], v[126:129], v[64:79]
	ds_read_b64_tr_b16 v[240:241], v154 offset:8192
	ds_read_b64_tr_b16 v[242:243], v154 offset:10240
	s_add_i32 m0, s1, 0xc400
	s_nop 0
	global_load_lds_dwordx4 v168, s[98:99]
	s_waitcnt lgkmcnt(7)
	v_mfma_f32_32x32x16_bf16 v[80:95], v[146:149], v[130:133], v[80:95]
	ds_read_b64_tr_b16 v[244:245], v154 offset:12288
	ds_read_b64_tr_b16 v[246:247], v154 offset:14336
	s_waitcnt lgkmcnt(8)
	v_mfma_f32_32x32x16_bf16 v[64:79], v[150:153], v[130:133], v[64:79]
	ds_read_b64_tr_b16 v[248:249], v154 offset:512
	ds_read_b64_tr_b16 v[250:251], v154 offset:2560
	s_waitcnt lgkmcnt(8)
	v_mfma_f32_32x32x16_bf16 v[0:15], v[104:107], v[176:179], v[0:15]
	ds_read_b64_tr_b16 v[234:235], v154 offset:4608
	ds_read_b64_tr_b16 v[236:237], v154 offset:6656
	s_waitcnt lgkmcnt(8)
	v_mfma_f32_32x32x16_bf16 v[0:15], v[108:111], v[180:183], v[0:15]
	ds_read_b64_tr_b16 v[146:147], v154 offset:8704
	ds_read_b64_tr_b16 v[148:149], v154 offset:10752
	v_exp_f32_e32 v212, v80
	v_exp_f32_e32 v214, v81
	v_exp_f32_e32 v210, v82
	s_waitcnt lgkmcnt(8)
; #define SBAR() __builtin_amdgcn_sched_barrier(0)
; #define NAM(P0, P1, t) do { if constexpr (NA) na_mask(P0, P1, kr_lo + (t), r0, qrow, qc, c0, hi, bl); } while (0)
; #define PSM(P0, P1, MN, AL) do { if constexpr (NA) partialSM(P0, P1, m_reg, MN, AL); else { AL = 1.f; _Pragma("unroll") for (int r = 0; r < 16; ++r) P0[r] = __builtin_amdgcn_exp2f(P0[r]); } } while (0)
; #define RESCN(a) do { if constexpr (NA) RESC(a); } while (0)
; #define VM0() asm volatile("s_waitcnt vmcnt(0)" ::: "memory")
; #define NAM(P0, P1, t) do { if constexpr (NA) na_mask(P0, P1, kr_lo + (t), r0, qrow, qc, c0, hi, bl); } while (0)
; #define PSM(P0, P1, MN, AL) do { if constexpr (NA) partialSM(P0, P1, m_reg, MN, AL); else { AL = 1.f; _Pragma("unroll") for (int r = 0; r < 16; ++r) P0[r] = __builtin_amdgcn_exp2f(P0[r]); } } while (0)
; #define RESCN(a) do { if constexpr (NA) RESC(a); } while (0)
; template <bool NA, int ROWB>
; __device__ __forceinline__ void attn_dma(const bf16* __restrict__ Qb, const bf16* __restrict__ Kh, const bf16* __restrict__ Vh, bf16* __restrict__ Ob, int NT, char* lds, const int tid, float* __restrict__ ssb, int qrow0, int kr_lo, const float* bl) {
;     ...
;   for (int t = 1; t + 1 < NT; t += 2) {
;     DMA_TILE(t + 1, bn);
;     SBAR(); qkt<false>(pB0, pB1, (const bf16*)(K_lds + bc * SHM_K), qr, nullptr, r32, hi); NAM(pB0, pB1, t);
;     finishSM(pA0, pA1, alA, l_reg, pa0, pa1, pa2, pa3); SBAR();
;     pv_d0(o, vb0 + bp * (int)SHM_V, pa0, pa1, pa2, pa3); PSM(pB0, pB1, mnB, alB); RESCN(alB);
;     VM0(); __syncthreads();
;     bp = bc; bc = bn; bn = NEXTB(bn);
;     if (t + 2 < NT) DMA_TILE(t + 2, bn);
;     SBAR(); qkt<false>(pA0, pA1, (const bf16*)(K_lds + bc * SHM_K), qr, nullptr, r32, hi); NAM(pA0, pA1, t + 1);
;     finishSM(pB0, pB1, alB, l_reg, pa0, pa1, pa2, pa3); SBAR();
;     pv_d0(o, vb0 + bp * (int)SHM_V, pa0, pa1, pa2, pa3); PSM(pA0, pA1, mnA, alA); RESCN(alA);
;     VM0(); __syncthreads();
;     bp = bc; bc = bn; bn = NEXTB(bn);
;   }
;   SBAR(); qkt<false>(pB0, pB1, (const bf16*)(K_lds + bc * SHM_K), qr, nullptr, r32, hi); NAM(pB0, pB1, NT - 1);
;   finishSM(pA0, pA1, alA, l_reg, pa0, pa1, pa2, pa3); SBAR();
;   pv_d0(o, vb0 + bp * (int)SHM_V, pa0, pa1, pa2, pa3); PSM(pB0, pB1, mnB, alB); RESCN(alB);
;   finishSM(pB0, pB1, alB, l_reg, pa0, pa1, pa2, pa3); SBAR();
;   pv_d0(o, vb0 + bc * (int)SHM_V, pa0, pa1, pa2, pa3);
	v_mfma_f32_32x32x16_bf16 v[0:15], v[96:99], v[240:243], v[0:15]
	ds_read_b64_tr_b16 v[150:151], v154 offset:12800
	ds_read_b64_tr_b16 v[152:153], v154 offset:14848
	v_exp_f32_e32 v213, v83
	v_exp_f32_e32 v208, v84
	v_exp_f32_e32 v211, v85
	s_waitcnt lgkmcnt(8)
	v_mfma_f32_32x32x16_bf16 v[0:15], v[100:103], v[244:247], v[0:15]
	ds_read_b64_tr_b16 v[176:177], v154 offset:1024
	ds_read_b64_tr_b16 v[178:179], v154 offset:3072
	v_exp_f32_e32 v207, v86
	v_exp_f32_e32 v209, v87
	v_exp_f32_e32 v203, v88
	s_waitcnt lgkmcnt(8)
	v_mfma_f32_32x32x16_bf16 v[16:31], v[104:107], v[248:251], v[16:31]
	ds_read_b64_tr_b16 v[180:181], v154 offset:5120
	ds_read_b64_tr_b16 v[182:183], v154 offset:7168
	v_exp_f32_e32 v206, v89
	v_exp_f32_e32 v198, v90
	v_exp_f32_e32 v205, v91
	s_waitcnt lgkmcnt(8)
	v_mfma_f32_32x32x16_bf16 v[16:31], v[108:111], v[234:237], v[16:31]
	ds_read_b64_tr_b16 v[240:241], v154 offset:9216
	ds_read_b64_tr_b16 v[242:243], v154 offset:11264
	v_exp_f32_e32 v196, v92
	v_exp_f32_e32 v199, v93
	v_exp_f32_e32 v175, v94
	s_add_i32 m0, s25, 0x400
	s_nop 0
	global_load_lds_dwordx4 v170, s[100:101]
	s_waitcnt lgkmcnt(8)
	v_mfma_f32_32x32x16_bf16 v[16:31], v[96:99], v[146:149], v[16:31]
	ds_read_b64_tr_b16 v[244:245], v154 offset:13312
	ds_read_b64_tr_b16 v[246:247], v154 offset:15360
	v_exp_f32_e32 v197, v95
	v_exp_f32_e32 v64, v64
	v_exp_f32_e32 v65, v65
	s_waitcnt lgkmcnt(8)
	v_mfma_f32_32x32x16_bf16 v[16:31], v[100:103], v[150:153], v[16:31]
	ds_read_b64_tr_b16 v[248:249], v154 offset:1536
	ds_read_b64_tr_b16 v[250:251], v154 offset:3584
	v_exp_f32_e32 v66, v66
	v_exp_f32_e32 v67, v67
	v_exp_f32_e32 v68, v68
	s_waitcnt lgkmcnt(8)
	v_mfma_f32_32x32x16_bf16 v[32:47], v[104:107], v[176:179], v[32:47]
	ds_read_b64_tr_b16 v[234:235], v154 offset:5632
	ds_read_b64_tr_b16 v[236:237], v154 offset:7680
	v_exp_f32_e32 v69, v69
	v_exp_f32_e32 v70, v70
	v_exp_f32_e32 v71, v71
	s_waitcnt lgkmcnt(8)
	v_mfma_f32_32x32x16_bf16 v[32:47], v[108:111], v[180:183], v[32:47]
	ds_read_b64_tr_b16 v[146:147], v154 offset:9728
	ds_read_b64_tr_b16 v[148:149], v154 offset:11776
	v_exp_f32_e32 v72, v72
	v_exp_f32_e32 v73, v73
	s_waitcnt lgkmcnt(8)
	v_mfma_f32_32x32x16_bf16 v[32:47], v[96:99], v[240:243], v[32:47]
	ds_read_b64_tr_b16 v[150:151], v154 offset:13824
	ds_read_b64_tr_b16 v[152:153], v154 offset:15872
	v_exp_f32_e32 v74, v74
	v_exp_f32_e32 v75, v75
	s_waitcnt lgkmcnt(8)
	v_mfma_f32_32x32x16_bf16 v[32:47], v[100:103], v[244:247], v[32:47]
	v_exp_f32_e32 v76, v76
	v_exp_f32_e32 v77, v77
	s_waitcnt lgkmcnt(6)
	v_mfma_f32_32x32x16_bf16 v[48:63], v[104:107], v[248:251], v[48:63]
	v_exp_f32_e32 v78, v78
	v_exp_f32_e32 v79, v79
	s_waitcnt vmcnt(4) lgkmcnt(0)
	s_barrier
	s_add_i32 s16, s16, 2
	s_cmpk_gt_u32 s16, 0x7c
	s_cbranch_scc0 .Lgqa_top
	v_mfma_f32_32x32x16_bf16 v[48:63], v[108:111], v[234:237], v[48:63]
	v_mfma_f32_32x32x16_bf16 v[48:63], v[96:99], v[146:149], v[48:63]
	v_mfma_f32_32x32x16_bf16 v[48:63], v[100:103], v[150:153], v[48:63]
	s_waitcnt vmcnt(0)
	s_barrier
	v_mov_b32_e32 v161, v112
	s_nop 1
	v_permlane32_swap_b32_e32 v112, v161
	v_add_f32_e32 v112, v112, v161
	s_add_i32 s0, 0, 0x10000
	v_add_u32_e32 v84, s0, v187
	ds_read_b128 v[80:83], v84
	ds_read_b128 v[154:157], v84 offset:8192
	v_add_u32_e32 v100, s0, v188
	ds_read_b128 v[96:99], v100
	ds_read_b128 v[158:161], v100 offset:8192
	v_add_u32_e32 v100, s0, v189
	s_waitcnt lgkmcnt(3)
	v_mfma_f32_32x32x16_bf16 v[80:95], v[80:83], v[138:141], 0
	s_nop 0
	v_mov_b32_e32 v180, v66
	v_mov_b32_e32 v181, v67
	v_mov_b32_e32 v182, v68
	v_mov_b32_e32 v183, v69
	v_mov_b32_e32 v215, v70
	v_mov_b32_e32 v216, v71
	v_mov_b32_e32 v217, v72
	s_waitcnt lgkmcnt(1)
	v_mfma_f32_32x32x16_bf16 v[80:95], v[96:99], v[142:145], v[80:95]
	ds_read_b128 v[96:99], v100
	ds_read_b128 v[150:153], v100 offset:8192
	v_mov_b32_e32 v218, v73
	v_mov_b32_e32 v219, v74
	v_mov_b32_e32 v220, v75
	v_mov_b32_e32 v221, v76
	v_mov_b32_e32 v222, v77
	v_mov_b32_e32 v223, v78
	s_waitcnt lgkmcnt(1)
	v_mfma_f32_32x32x16_bf16 v[80:95], v[96:99], v[134:137], v[80:95]
	v_add_u32_e32 v96, s0, v190
	ds_read_b128 v[100:103], v96
	ds_read_b128 v[96:99], v96 offset:8192
	v_mov_b32_e32 v79, v79
	s_waitcnt lgkmcnt(1)
	v_mfma_f32_32x32x16_bf16 v[80:95], v[100:103], v[114:117], v[80:95]
	v_add_u32_e32 v100, s0, v191
	ds_read_b128 v[104:107], v100
	ds_read_b128 v[100:103], v100 offset:8192
	s_waitcnt lgkmcnt(1)
	v_mfma_f32_32x32x16_bf16 v[80:95], v[104:107], v[118:121], v[80:95]
	v_add_u32_e32 v104, s0, v192
	ds_read_b128 v[108:111], v104
	ds_read_b128 v[104:107], v104 offset:8192
	s_waitcnt lgkmcnt(1)
	v_mfma_f32_32x32x16_bf16 v[80:95], v[108:111], v[122:125], v[80:95]
	v_add_u32_e32 v108, s0, v193
	ds_read_b128 v[146:149], v108
	ds_read_b128 v[108:111], v108 offset:8192
	s_waitcnt lgkmcnt(1)
	v_mfma_f32_32x32x16_bf16 v[80:95], v[146:149], v[126:129], v[80:95]
	v_add_u32_e32 v146, s0, v194
	ds_read_b128 v[176:179], v146
	ds_read_b128 v[146:149], v146 offset:8192
	s_waitcnt lgkmcnt(1)
; #define SBAR() __builtin_amdgcn_sched_barrier(0)
; #define NAM(P0, P1, t) do { if constexpr (NA) na_mask(P0, P1, kr_lo + (t), r0, qrow, qc, c0, hi, bl); } while (0)
; #define PSM(P0, P1, MN, AL) do { if constexpr (NA) partialSM(P0, P1, m_reg, MN, AL); else { AL = 1.f; _Pragma("unroll") for (int r = 0; r < 16; ++r) P0[r] = __builtin_amdgcn_exp2f(P0[r]); } } while (0)
; #define RESCN(a) do { if constexpr (NA) RESC(a); } while (0)
; #define NAM(P0, P1, t) do { if constexpr (NA) na_mask(P0, P1, kr_lo + (t), r0, qrow, qc, c0, hi, bl); } while (0)
; #define PSM(P0, P1, MN, AL) do { if constexpr (NA) partialSM(P0, P1, m_reg, MN, AL); else { AL = 1.f; _Pragma("unroll") for (int r = 0; r < 16; ++r) P0[r] = __builtin_amdgcn_exp2f(P0[r]); } } while (0)
; #define RESCN(a) do { if constexpr (NA) RESC(a); } while (0)
; __device__ __forceinline__ void finishSM(f32x16& p0, f32x16& p1, float alpha, float& l_reg, bf16x8& pa0, bf16x8& pa1, bf16x8& pa2, bf16x8& pa3) {
;   for (int r = 0; r < 16; ++r) p1[r] = __builtin_amdgcn_exp2f(p1[r]);
;   float ps = 0; for (int r = 0; r < 16; ++r) ps += p0[r]; for (int r = 0; r < 16; ++r) ps += p1[r];
;   { auto rr = __builtin_amdgcn_permlane32_swap(__float_as_uint(ps), __float_as_uint(ps), false, false);
;     ps = __uint_as_float(rr[0]) + __uint_as_float(rr[1]); }
;   l_reg = l_reg * alpha + ps;
;     ...
;   PK4(p0, 0, pa0); PK4(p0, 8, pa1); PK4(p1, 0, pa2); PK4(p1, 8, pa3);
; template <bool NA, int ROWB>
; __device__ __forceinline__ void attn_dma(const bf16* __restrict__ Qb, const bf16* __restrict__ Kh, const bf16* __restrict__ Vh, bf16* __restrict__ Ob, int NT, char* lds, const int tid, float* __restrict__ ssb, int qrow0, int kr_lo, const float* bl) {
;     ...
;   SBAR(); qkt<false>(pB0, pB1, (const bf16*)(K_lds + bc * SHM_K), qr, nullptr, r32, hi); NAM(pB0, pB1, NT - 1);
;   finishSM(pA0, pA1, alA, l_reg, pa0, pa1, pa2, pa3); SBAR();
;   pv_d0(o, vb0 + bp * (int)SHM_V, pa0, pa1, pa2, pa3); PSM(pB0, pB1, mnB, alB); RESCN(alB);
;   finishSM(pB0, pB1, alB, l_reg, pa0, pa1, pa2, pa3); SBAR();
;   pv_d0(o, vb0 + bc * (int)SHM_V, pa0, pa1, pa2, pa3);
	v_mfma_f32_32x32x16_bf16 v[80:95], v[176:179], v[130:133], v[80:95]
	v_mov_b32_e32 v177, v64
	v_add_f32_e32 v64, 0, v212
	v_add_f32_e32 v64, v214, v64
	v_add_f32_e32 v64, v210, v64
	v_add_f32_e32 v64, v213, v64
	v_add_f32_e32 v64, v208, v64
	v_add_f32_e32 v64, v211, v64
	v_add_f32_e32 v64, v207, v64
	v_add_f32_e32 v64, v209, v64
	v_add_f32_e32 v64, v203, v64
	v_add_f32_e32 v64, v206, v64
	v_add_f32_e32 v64, v198, v64
	v_add_f32_e32 v64, v205, v64
	v_add_f32_e32 v64, v196, v64
	v_mov_b32_e32 v179, v65
	v_add_f32_e32 v64, v199, v64
	v_add_f32_e32 v64, v175, v64
	v_add_f32_e32 v64, v197, v64
	v_add_f32_e32 v64, v64, v177
	v_add_f32_e32 v64, v179, v64
	v_add_f32_e32 v64, v180, v64
	v_add_f32_e32 v64, v181, v64
	v_add_f32_e32 v64, v182, v64
	v_add_f32_e32 v64, v183, v64
	v_add_f32_e32 v64, v215, v64
	v_add_f32_e32 v64, v216, v64
	v_add_f32_e32 v64, v217, v64
	v_add_f32_e32 v64, v218, v64
	v_add_f32_e32 v64, v219, v64
	v_add_f32_e32 v64, v220, v64
	v_add_f32_e32 v64, v221, v64
	v_add_f32_e32 v64, v222, v64
	v_add_f32_e32 v64, v223, v64
	v_add_f32_e32 v176, v79, v64
	v_mov_b32_e32 v178, v176
	s_nop 1
	v_permlane32_swap_b32_e32 v176, v178
	v_cvt_pk_bf16_f32 v64, v212, v214
	v_cvt_pk_bf16_f32 v65, v210, v213
	v_cvt_pk_bf16_f32 v66, v208, v211
	v_cvt_pk_bf16_f32 v67, v207, v209
	v_cvt_pk_bf16_f32 v68, v203, v206
	v_cvt_pk_bf16_f32 v69, v198, v205
	v_cvt_pk_bf16_f32 v70, v196, v199
	v_cvt_pk_bf16_f32 v71, v175, v197
	v_cvt_pk_bf16_f32 v72, v177, v179
	v_cvt_pk_bf16_f32 v73, v180, v181
	v_cvt_pk_bf16_f32 v74, v182, v183
	v_cvt_pk_bf16_f32 v75, v215, v216
	v_cvt_pk_bf16_f32 v76, v217, v218
	v_cvt_pk_bf16_f32 v77, v219, v220
	v_cvt_pk_bf16_f32 v78, v221, v222
	v_cvt_pk_bf16_f32 v79, v223, v79
	s_nop 0
	ds_read_b64_tr_b16 v[180:181], v195 offset:0
	ds_read_b64_tr_b16 v[182:183], v195 offset:0x800
	ds_read_b64_tr_b16 v[196:197], v195 offset:0x1000
	ds_read_b64_tr_b16 v[198:199], v195 offset:0x1800
	ds_read_b64_tr_b16 v[206:207], v195 offset:0x2000
	ds_read_b64_tr_b16 v[208:209], v195 offset:0x2800
	ds_read_b64_tr_b16 v[210:211], v195 offset:0x3000
	ds_read_b64_tr_b16 v[212:213], v195 offset:0x3800
	s_waitcnt lgkmcnt(0)
	s_nop 0
	v_mfma_f32_32x32x16_bf16 v[0:15], v[64:67], v[180:183], v[0:15]
	ds_read_b64_tr_b16 v[180:181], v195 offset:0x200
	ds_read_b64_tr_b16 v[182:183], v195 offset:0xa00
	v_mfma_f32_32x32x16_bf16 v[0:15], v[68:71], v[196:199], v[0:15]
	ds_read_b64_tr_b16 v[196:197], v195 offset:0x1200
	ds_read_b64_tr_b16 v[198:199], v195 offset:0x1a00
	v_mfma_f32_32x32x16_bf16 v[0:15], v[72:75], v[206:209], v[0:15]
	ds_read_b64_tr_b16 v[206:207], v195 offset:0x2200
	ds_read_b64_tr_b16 v[208:209], v195 offset:0x2a00
	v_mfma_f32_32x32x16_bf16 v[0:15], v[76:79], v[210:213], v[0:15]
	ds_read_b64_tr_b16 v[210:211], v195 offset:0x3200
	ds_read_b64_tr_b16 v[212:213], v195 offset:0x3a00
	s_waitcnt lgkmcnt(0)
	v_mfma_f32_32x32x16_bf16 v[16:31], v[64:67], v[180:183], v[16:31]
	ds_read_b64_tr_b16 v[180:181], v195 offset:0x400
	ds_read_b64_tr_b16 v[182:183], v195 offset:0xc00
	v_mfma_f32_32x32x16_bf16 v[16:31], v[68:71], v[196:199], v[16:31]
	ds_read_b64_tr_b16 v[196:197], v195 offset:0x1400
	ds_read_b64_tr_b16 v[198:199], v195 offset:0x1c00
	v_mfma_f32_32x32x16_bf16 v[16:31], v[72:75], v[206:209], v[16:31]
	ds_read_b64_tr_b16 v[206:207], v195 offset:0x2400
	ds_read_b64_tr_b16 v[208:209], v195 offset:0x2c00
	v_mfma_f32_32x32x16_bf16 v[16:31], v[76:79], v[210:213], v[16:31]
	ds_read_b64_tr_b16 v[210:211], v195 offset:0x3400
	ds_read_b64_tr_b16 v[212:213], v195 offset:0x3c00
	s_waitcnt lgkmcnt(0)
	v_mfma_f32_32x32x16_bf16 v[32:47], v[64:67], v[180:183], v[32:47]
	ds_read_b64_tr_b16 v[180:181], v195 offset:0x600
	ds_read_b64_tr_b16 v[182:183], v195 offset:0xe00
	v_mfma_f32_32x32x16_bf16 v[32:47], v[68:71], v[196:199], v[32:47]
	ds_read_b64_tr_b16 v[196:197], v195 offset:0x1600
	ds_read_b64_tr_b16 v[198:199], v195 offset:0x1e00
	v_mfma_f32_32x32x16_bf16 v[32:47], v[72:75], v[206:209], v[32:47]
	ds_read_b64_tr_b16 v[206:207], v195 offset:0x2600
	ds_read_b64_tr_b16 v[208:209], v195 offset:0x2e00
	v_mfma_f32_32x32x16_bf16 v[32:47], v[76:79], v[210:213], v[32:47]
	ds_read_b64_tr_b16 v[210:211], v195 offset:0x3600
	ds_read_b64_tr_b16 v[212:213], v195 offset:0x3e00
	s_waitcnt lgkmcnt(0)
	v_mfma_f32_32x32x16_bf16 v[48:63], v[64:67], v[180:183], v[48:63]
	v_exp_f32_e32 v175, v80
	v_exp_f32_e32 v180, v81
	v_exp_f32_e32 v181, v82
	v_exp_f32_e32 v182, v83
	v_exp_f32_e32 v183, v84
	v_exp_f32_e32 v80, v90
	v_exp_f32_e32 v86, v86
	v_mfma_f32_32x32x16_bf16 v[48:63], v[68:71], v[196:199], v[48:63]
	v_exp_f32_e32 v196, v85
	v_exp_f32_e32 v87, v87
	v_exp_f32_e32 v88, v88
	v_exp_f32_e32 v89, v89
	v_exp_f32_e32 v81, v91
	v_exp_f32_e32 v82, v92
	v_exp_f32_e32 v83, v93
	v_mfma_f32_32x32x16_bf16 v[48:63], v[72:75], v[206:209], v[48:63]
	v_exp_f32_e32 v84, v94
	v_exp_f32_e32 v85, v95
	v_mfma_f32_32x32x16_bf16 v[48:63], v[76:79], v[210:213], v[48:63]
	v_mfma_f32_32x32x16_bf16 v[64:79], v[154:157], v[138:141], 0
	v_mfma_f32_32x32x16_bf16 v[64:79], v[158:161], v[142:145], v[64:79]
	v_mfma_f32_32x32x16_bf16 v[64:79], v[150:153], v[134:137], v[64:79]
	v_mfma_f32_32x32x16_bf16 v[64:79], v[96:99], v[114:117], v[64:79]
	v_mfma_f32_32x32x16_bf16 v[64:79], v[100:103], v[118:121], v[64:79]
	v_mfma_f32_32x32x16_bf16 v[64:79], v[104:107], v[122:125], v[64:79]
	v_mfma_f32_32x32x16_bf16 v[64:79], v[108:111], v[126:129], v[64:79]
	s_waitcnt lgkmcnt(0)
; #define SBAR() __builtin_amdgcn_sched_barrier(0)
; __device__ __forceinline__ int crow(int r, int hi) { return (r & 3) + 8 * (r >> 2) + 4 * hi; }
; #define PSM(P0, P1, MN, AL) do { if constexpr (NA) partialSM(P0, P1, m_reg, MN, AL); else { AL = 1.f; _Pragma("unroll") for (int r = 0; r < 16; ++r) P0[r] = __builtin_amdgcn_exp2f(P0[r]); } } while (0)
; #define RESCN(a) do { if constexpr (NA) RESC(a); } while (0)
; #define PSM(P0, P1, MN, AL) do { if constexpr (NA) partialSM(P0, P1, m_reg, MN, AL); else { AL = 1.f; _Pragma("unroll") for (int r = 0; r < 16; ++r) P0[r] = __builtin_amdgcn_exp2f(P0[r]); } } while (0)
; #define RESCN(a) do { if constexpr (NA) RESC(a); } while (0)
; template <bool NA, int ROWB>
; __device__ __forceinline__ void attn_dma(const bf16* __restrict__ Qb, const bf16* __restrict__ Kh, const bf16* __restrict__ Vh, bf16* __restrict__ Ob, int NT, char* lds, const int tid, float* __restrict__ ssb, int qrow0, int kr_lo, const float* bl) {
;     ...
;   pv_d0(o, vb0 + bp * (int)SHM_V, pa0, pa1, pa2, pa3); PSM(pB0, pB1, mnB, alB); RESCN(alB);
;   finishSM(pB0, pB1, alB, l_reg, pa0, pa1, pa2, pa3); SBAR();
;   pv_d0(o, vb0 + bc * (int)SHM_V, pa0, pa1, pa2, pa3);
;   if (hi == 0) li_l[r32] = l_reg; asm volatile("s_waitcnt lgkmcnt(0)" ::: "memory");
;   float rli[16];
; #pragma unroll
;   for (int r = 0; r < 16; ++r) rli[r] = __builtin_amdgcn_rcpf(li_l[crow(r, hi)]);
	v_mfma_f32_32x32x16_bf16 v[64:79], v[146:149], v[130:133], v[64:79]
	s_nop 11
	v_exp_f32_e32 v90, v64
	v_add_f32_e32 v64, 0, v175
	v_add_f32_e32 v64, v180, v64
	v_add_f32_e32 v64, v181, v64
	v_add_f32_e32 v64, v182, v64
	v_add_f32_e32 v64, v183, v64
	v_add_f32_e32 v64, v196, v64
	v_add_f32_e32 v64, v86, v64
	v_add_f32_e32 v64, v87, v64
	v_add_f32_e32 v64, v88, v64
	v_add_f32_e32 v64, v89, v64
	v_add_f32_e32 v64, v80, v64
	v_add_f32_e32 v64, v81, v64
	v_add_f32_e32 v64, v82, v64
	v_exp_f32_e32 v91, v65
	v_add_f32_e32 v64, v83, v64
	v_exp_f32_e32 v92, v66
	v_add_f32_e32 v64, v84, v64
	v_exp_f32_e32 v93, v67
	v_add_f32_e32 v64, v85, v64
	v_exp_f32_e32 v94, v68
	v_add_f32_e32 v64, v64, v90
	v_exp_f32_e32 v95, v69
	v_add_f32_e32 v64, v91, v64
	v_exp_f32_e32 v96, v70
	v_add_f32_e32 v64, v92, v64
	v_exp_f32_e32 v97, v71
	v_add_f32_e32 v64, v93, v64
	v_exp_f32_e32 v98, v72
	v_add_f32_e32 v64, v94, v64
	v_exp_f32_e32 v99, v73
	v_add_f32_e32 v64, v95, v64
	v_exp_f32_e32 v100, v74
	v_add_f32_e32 v64, v96, v64
	v_exp_f32_e32 v101, v75
	v_add_f32_e32 v64, v97, v64
	v_exp_f32_e32 v102, v76
	v_add_f32_e32 v64, v98, v64
	v_exp_f32_e32 v103, v77
	v_add_f32_e32 v64, v99, v64
	v_exp_f32_e32 v104, v78
	v_add_f32_e32 v64, v100, v64
	v_exp_f32_e32 v79, v79
	v_add_f32_e32 v64, v101, v64
	v_add_f32_e32 v64, v102, v64
	v_add_f32_e32 v64, v103, v64
	v_add_f32_e32 v64, v104, v64
	v_add_f32_e32 v177, v79, v64
	v_mov_b32_e32 v179, v177
	s_nop 1
	v_permlane32_swap_b32_e32 v177, v179
	v_cvt_pk_bf16_f32 v64, v175, v180
	v_cvt_pk_bf16_f32 v65, v181, v182
	v_cvt_pk_bf16_f32 v66, v183, v196
	v_cvt_pk_bf16_f32 v67, v86, v87
	v_cvt_pk_bf16_f32 v68, v88, v89
	v_cvt_pk_bf16_f32 v69, v80, v81
	v_cvt_pk_bf16_f32 v70, v82, v83
	v_cvt_pk_bf16_f32 v71, v84, v85
	v_cvt_pk_bf16_f32 v72, v90, v91
	v_cvt_pk_bf16_f32 v73, v92, v93
	v_cvt_pk_bf16_f32 v74, v94, v95
	v_cvt_pk_bf16_f32 v75, v96, v97
	v_cvt_pk_bf16_f32 v76, v98, v99
	v_cvt_pk_bf16_f32 v77, v100, v101
	v_cvt_pk_bf16_f32 v78, v102, v103
	v_cvt_pk_bf16_f32 v79, v104, v79
	s_nop 0
	ds_read_b64_tr_b16 v[80:81], v201 offset:0
	ds_read_b64_tr_b16 v[82:83], v201 offset:0x800
	ds_read_b64_tr_b16 v[84:85], v201 offset:0x1000
	ds_read_b64_tr_b16 v[86:87], v201 offset:0x1800
	ds_read_b64_tr_b16 v[88:89], v201 offset:0x2000
	ds_read_b64_tr_b16 v[90:91], v201 offset:0x2800
	ds_read_b64_tr_b16 v[92:93], v201 offset:0x3000
	ds_read_b64_tr_b16 v[94:95], v201 offset:0x3800
	s_waitcnt lgkmcnt(0)
	s_nop 0
	v_mfma_f32_32x32x16_bf16 v[0:15], v[64:67], v[80:83], v[0:15]
	ds_read_b64_tr_b16 v[80:81], v201 offset:0x200
	ds_read_b64_tr_b16 v[82:83], v201 offset:0xa00
	v_mfma_f32_32x32x16_bf16 v[0:15], v[68:71], v[84:87], v[0:15]
	ds_read_b64_tr_b16 v[84:85], v201 offset:0x1200
	ds_read_b64_tr_b16 v[86:87], v201 offset:0x1a00
	v_mfma_f32_32x32x16_bf16 v[0:15], v[72:75], v[88:91], v[0:15]
	ds_read_b64_tr_b16 v[88:89], v201 offset:0x2200
	ds_read_b64_tr_b16 v[90:91], v201 offset:0x2a00
	v_mfma_f32_32x32x16_bf16 v[0:15], v[76:79], v[92:95], v[0:15]
	ds_read_b64_tr_b16 v[92:93], v201 offset:0x3200
	ds_read_b64_tr_b16 v[94:95], v201 offset:0x3a00
	s_waitcnt lgkmcnt(0)
	v_mfma_f32_32x32x16_bf16 v[16:31], v[64:67], v[80:83], v[16:31]
	ds_read_b64_tr_b16 v[80:81], v201 offset:0x400
	ds_read_b64_tr_b16 v[82:83], v201 offset:0xc00
	v_mfma_f32_32x32x16_bf16 v[16:31], v[68:71], v[84:87], v[16:31]
	ds_read_b64_tr_b16 v[84:85], v201 offset:0x1400
	ds_read_b64_tr_b16 v[86:87], v201 offset:0x1c00
	v_mfma_f32_32x32x16_bf16 v[16:31], v[72:75], v[88:91], v[16:31]
	ds_read_b64_tr_b16 v[88:89], v201 offset:0x2400
	ds_read_b64_tr_b16 v[90:91], v201 offset:0x2c00
	v_mfma_f32_32x32x16_bf16 v[16:31], v[76:79], v[92:95], v[16:31]
	ds_read_b64_tr_b16 v[92:93], v201 offset:0x3400
	ds_read_b64_tr_b16 v[94:95], v201 offset:0x3c00
	s_waitcnt lgkmcnt(0)
	v_mfma_f32_32x32x16_bf16 v[32:47], v[64:67], v[80:83], v[32:47]
	ds_read_b64_tr_b16 v[80:81], v201 offset:0x600
	ds_read_b64_tr_b16 v[82:83], v201 offset:0xe00
	v_mfma_f32_32x32x16_bf16 v[32:47], v[68:71], v[84:87], v[32:47]
	ds_read_b64_tr_b16 v[84:85], v201 offset:0x1600
	ds_read_b64_tr_b16 v[86:87], v201 offset:0x1e00
	v_mfma_f32_32x32x16_bf16 v[32:47], v[72:75], v[88:91], v[32:47]
	ds_read_b64_tr_b16 v[88:89], v201 offset:0x2600
	ds_read_b64_tr_b16 v[90:91], v201 offset:0x2e00
	v_mfma_f32_32x32x16_bf16 v[32:47], v[76:79], v[92:95], v[32:47]
	ds_read_b64_tr_b16 v[92:93], v201 offset:0x3600
	ds_read_b64_tr_b16 v[94:95], v201 offset:0x3e00
	s_waitcnt lgkmcnt(0)
	v_mfma_f32_32x32x16_bf16 v[48:63], v[64:67], v[80:83], v[48:63]
	v_mfma_f32_32x32x16_bf16 v[48:63], v[68:71], v[84:87], v[48:63]
	v_mfma_f32_32x32x16_bf16 v[48:63], v[72:75], v[88:91], v[48:63]
	v_mfma_f32_32x32x16_bf16 v[48:63], v[76:79], v[92:95], v[48:63]
	s_and_saveexec_b64 s[4:5], vcc
	v_pk_add_f32 v[64:65], v[176:177], v[178:179]
	s_nop 0
	v_add_f32_e32 v64, v112, v64
	v_add_f32_e32 v64, v64, v65
	ds_write_b32 v204, v64
	s_or_b64 exec, exec, s[4:5]
	s_lshl_b64 s[0:1], s[6:7], 12
	v_readlane_b32 s4, v254, 41
	s_waitcnt lgkmcnt(0)
	v_add_u32_e32 v72, v185, v186
	s_add_u32 s4, s4, s0
	v_readlane_b32 s0, v254, 42
	ds_read_b128 v[64:67], v72
	ds_read_b128 v[68:71], v72 offset:32
	s_addc_u32 s5, s0, s1
	s_lshl_b64 s[0:1], s[6:7], 6
	v_readlane_b32 s6, v254, 32
	v_readlane_b32 s7, v254, 33
	s_add_u32 s6, s6, s0
	s_addc_u32 s7, s7, s1
	s_lshl_b32 s0, s15, 1
	s_add_u32 s0, s4, s0
	s_waitcnt lgkmcnt(1)
	v_rcp_f32_e32 v84, v64
	s_addc_u32 s1, s5, 0
	v_mov_b32_e32 v74, v200
	v_rcp_f32_e32 v85, v65
	v_rcp_f32_e32 v86, v66
	v_rcp_f32_e32 v87, v67
	s_waitcnt lgkmcnt(0)
; __device__ __forceinline__ float xs(float v, int o, int lane) { return __int_as_float(__builtin_amdgcn_ds_bpermute((lane ^ o) << 2, __float_as_int(v))); }
; __device__ __forceinline__ void st16_wt(void* p, u32x4 v) { asm volatile("global_store_dwordx4 %0, %1, off sc0 sc1\n\ts_nop 1" :: "v"(p), "v"(v) : "memory"); }
; template <bool NA, int ROWB>
; __device__ __forceinline__ void attn_dma(const bf16* __restrict__ Qb, const bf16* __restrict__ Kh, const bf16* __restrict__ Vh, bf16* __restrict__ Ob, int NT, char* lds, const int tid, float* __restrict__ ssb, int qrow0, int kr_lo, const float* bl) {
;     ...
;   int tid_e = tid; asm volatile("" : "+v"(tid_e));
;   const int lane_e = tid_e & 63, wid_e = tid_e >> 6, r32_e = lane_e & 31, hi_e = lane_e >> 5;
;   char* sg = lds + 100 * 1024 + wid_e * 4096;
; #pragma unroll
;   for (int half = 0; half < 2; ++half) {
;     char* wb_e = sg + hi_e * 1024 + r32_e * 2 + hi_e * 64;
;     char* wb_o = sg + hi_e * 1024 + r32_e * 2 - hi_e * 64;
; #pragma unroll
;     for (int rr = 0; rr < 8; ++rr) { const int r = half * 8 + rr; const int rc = ((rr & 3) + 8 * (rr >> 2)) * 256;
; #pragma unroll
;       for (int d0 = 0; d0 < 4; ++d0) { const float v = o[d0][r] * rli[r]; *(bf16*)(((d0 & 1) ? wb_o : wb_e) + rc + d0 * 64) = (bf16)(cvtpk(v, v) & 0xffffu); } }
;     asm volatile("s_waitcnt lgkmcnt(0)" ::: "memory");
;     const char* rb_e = sg + (lane_e >> 4) * 256 + (lane_e & 15) * 16;
;     const char* rb_o = sg + (lane_e >> 4) * 256 + (((lane_e & 15) * 16) ^ 64);
;     bf16* gb = Ow + (long)(half * 16 + (lane_e >> 4)) * LDO + (lane_e & 15) * 8;
; #pragma unroll
;     for (int i = 0; i < 4; ++i) { const u32x4 w = *(const u32x4*)(((i & 1) ? rb_o : rb_e) + i * 1024); st16_wt(gb + (long)i * 4 * LDO, w);
;       float q = sumsq8(w); q += xs(q, 1, lane_e); q += xs(q, 2, lane_e); q += xs(q, 4, lane_e); q += xs(q, 8, lane_e);
;       if ((lane_e & 15) == 0) ssb[(size_t)(wid_e * QBLK + half * 16 + (lane_e >> 4) + 4 * i) * 16] = q; }
;     asm volatile("s_waitcnt lgkmcnt(0)" ::: "memory");
;   }
	v_rcp_f32_e32 v88, v68
	v_rcp_f32_e32 v89, v69
	v_rcp_f32_e32 v90, v70
	v_rcp_f32_e32 v91, v71
	ds_read_b128 v[68:71], v72 offset:64
	ds_read_b128 v[64:67], v72 offset:96
	v_lshl_add_u64 v[72:73], s[0:1], 0, v[172:173]
	v_readlane_b32 s0, v254, 20
	v_ashrrev_i32_e32 v78, 6, v74
	v_bfe_u32 v76, v74, 5, 1
	v_lshlrev_b32_e32 v80, 1, v74
	v_and_b32_e32 v93, 15, v74
	v_and_b32_e32 v75, 63, v74
	v_lshl_add_u32 v77, v78, 12, s0
	v_lshlrev_b32_e32 v79, 10, v76
	v_and_b32_e32 v80, 62, v80
	v_lshlrev_b32_e32 v112, 4, v93
	v_add3_u32 v79, v77, v79, v80
	v_lshlrev_b32_e32 v80, 6, v76
	v_bfe_u32 v92, v74, 4, 2
	v_lshl_add_u64 v[82:83], v[72:73], 0, v[112:113]
	v_lshlrev_b32_e32 v72, 2, v75
	v_mul_f32_e32 v0, v0, v84
	v_lshl_add_u32 v81, v92, 8, v77
	v_xor_b32_e32 v77, 4, v72
	v_xor_b32_e32 v76, 8, v72
	v_xor_b32_e32 v75, 16, v72
	v_xor_b32_e32 v74, 32, v72
	v_lshl_or_b32 v72, v78, 5, v92
	v_cvt_pk_bf16_f32 v0, v0, v0
	v_add_u32_e32 v78, v79, v80
	ds_write_b16 v78, v0
	v_mul_f32_e32 v0, v16, v84
	v_cvt_pk_bf16_f32 v0, v0, v0
	v_sub_u32_e32 v16, v79, v80
	ds_write_b16 v16, v0 offset:64
	v_mul_f32_e32 v0, v32, v84
	v_cvt_pk_bf16_f32 v0, v0, v0
	ds_write_b16 v78, v0 offset:128
	v_mul_f32_e32 v0, v48, v84
	v_cvt_pk_bf16_f32 v0, v0, v0
	ds_write_b16 v16, v0 offset:192
	v_mul_f32_e32 v0, v1, v85
	v_cvt_pk_bf16_f32 v0, v0, v0
	ds_write_b16 v78, v0 offset:256
	v_mul_f32_e32 v0, v17, v85
	v_cvt_pk_bf16_f32 v0, v0, v0
	ds_write_b16 v16, v0 offset:320
	v_mul_f32_e32 v0, v33, v85
	v_cvt_pk_bf16_f32 v0, v0, v0
	ds_write_b16 v78, v0 offset:384
	v_mul_f32_e32 v0, v49, v85
	v_cvt_pk_bf16_f32 v0, v0, v0
	ds_write_b16 v16, v0 offset:448
	v_mul_f32_e32 v0, v2, v86
	v_cvt_pk_bf16_f32 v0, v0, v0
	ds_write_b16 v78, v0 offset:512
	v_mul_f32_e32 v0, v18, v86
	v_cvt_pk_bf16_f32 v0, v0, v0
	ds_write_b16 v16, v0 offset:576
	v_mul_f32_e32 v0, v34, v86
	v_cvt_pk_bf16_f32 v0, v0, v0
	ds_write_b16 v78, v0 offset:640
	v_mul_f32_e32 v0, v50, v86
	v_cvt_pk_bf16_f32 v0, v0, v0
	ds_write_b16 v16, v0 offset:704
	v_mul_f32_e32 v0, v3, v87
	v_cvt_pk_bf16_f32 v0, v0, v0
	ds_write_b16 v78, v0 offset:768
	v_mul_f32_e32 v0, v19, v87
	v_cvt_pk_bf16_f32 v0, v0, v0
	ds_write_b16 v16, v0 offset:832
	v_mul_f32_e32 v0, v35, v87
	v_cvt_pk_bf16_f32 v0, v0, v0
	ds_write_b16 v78, v0 offset:896
	v_mul_f32_e32 v0, v51, v87
	v_cvt_pk_bf16_f32 v0, v0, v0
	ds_write_b16 v16, v0 offset:960
	v_mul_f32_e32 v0, v4, v88
	v_cvt_pk_bf16_f32 v0, v0, v0
	ds_write_b16 v78, v0 offset:2048
	v_mul_f32_e32 v0, v20, v88
	v_cvt_pk_bf16_f32 v0, v0, v0
	ds_write_b16 v16, v0 offset:2112
	v_mul_f32_e32 v0, v36, v88
	v_cvt_pk_bf16_f32 v0, v0, v0
	ds_write_b16 v78, v0 offset:2176
	v_mul_f32_e32 v0, v52, v88
	v_cvt_pk_bf16_f32 v0, v0, v0
	ds_write_b16 v16, v0 offset:2240
	v_mul_f32_e32 v0, v5, v89
	v_cvt_pk_bf16_f32 v0, v0, v0
	ds_write_b16 v78, v0 offset:2304
	v_mul_f32_e32 v0, v21, v89
	v_cvt_pk_bf16_f32 v0, v0, v0
	ds_write_b16 v16, v0 offset:2368
	v_mul_f32_e32 v0, v37, v89
	v_cvt_pk_bf16_f32 v0, v0, v0
	ds_write_b16 v78, v0 offset:2432
	v_mul_f32_e32 v0, v53, v89
	v_cvt_pk_bf16_f32 v0, v0, v0
	ds_write_b16 v16, v0 offset:2496
	v_mul_f32_e32 v0, v6, v90
	v_cvt_pk_bf16_f32 v0, v0, v0
	ds_write_b16 v78, v0 offset:2560
	v_mul_f32_e32 v0, v22, v90
	v_cvt_pk_bf16_f32 v0, v0, v0
	ds_write_b16 v16, v0 offset:2624
	v_mul_f32_e32 v0, v38, v90
	v_cvt_pk_bf16_f32 v0, v0, v0
	ds_write_b16 v78, v0 offset:2688
	v_mul_f32_e32 v0, v54, v90
	v_cvt_pk_bf16_f32 v0, v0, v0
	ds_write_b16 v16, v0 offset:2752
	v_mul_f32_e32 v0, v7, v91
	v_cvt_pk_bf16_f32 v0, v0, v0
	ds_write_b16 v78, v0 offset:2816
	v_mul_f32_e32 v0, v23, v91
	v_cvt_pk_bf16_f32 v0, v0, v0
	ds_write_b16 v16, v0 offset:2880
	v_mul_f32_e32 v0, v39, v91
	v_cvt_pk_bf16_f32 v0, v0, v0
	ds_write_b16 v78, v0 offset:2944
	v_mul_f32_e32 v0, v55, v91
	v_cvt_pk_bf16_f32 v0, v0, v0
	ds_write_b16 v16, v0 offset:3008
	s_waitcnt lgkmcnt(0)
	v_add_u32_e32 v2, v81, v112
	ds_read_b128 v[4:7], v2
	v_lshlrev_b32_e32 v0, 12, v92
	v_mov_b32_e32 v1, v113
	v_lshl_add_u64 v[0:1], v[82:83], 0, v[0:1]
	s_mov_b64 s[0:1], 0x800
	v_lshl_add_u64 v[0:1], v[0:1], 0, s[0:1]
	s_waitcnt lgkmcnt(0)
	global_store_dwordx4 v[0:1], v[4:7], off sc0 sc1
	s_nop 1
	v_lshlrev_b32_e32 v3, 16, v4
	v_and_b32_e32 v4, 0xffff0000, v4
	v_mul_f32_e32 v4, v4, v4
	v_fmac_f32_e32 v4, v3, v3
	v_lshlrev_b32_e32 v3, 16, v5
	v_and_b32_e32 v5, 0xffff0000, v5
	v_mul_f32_e32 v5, v5, v5
	v_fmac_f32_e32 v5, v3, v3
	v_add_f32_e32 v3, v4, v5
	v_and_b32_e32 v5, 0xffff0000, v6
	v_lshlrev_b32_e32 v4, 16, v6
	v_mul_f32_e32 v5, v5, v5
	v_fmac_f32_e32 v5, v4, v4
	v_add_f32_e32 v3, v5, v3
	v_and_b32_e32 v5, 0xffff0000, v7
	v_lshlrev_b32_e32 v4, 16, v7
	v_mul_f32_e32 v5, v5, v5
	v_fmac_f32_e32 v5, v4, v4
	v_add_f32_e32 v3, v5, v3
	ds_bpermute_b32 v4, v77, v3
	s_lshl_b32 s4, s14, 2
	s_add_u32 s4, s6, s4
	s_addc_u32 s5, s7, 0
	s_add_u32 s6, s4, 0x25cc0020
	s_waitcnt lgkmcnt(0)
	v_add_f32_e32 v3, v3, v4
	ds_bpermute_b32 v4, v76, v3
	s_addc_u32 s7, s5, 0
	v_cmp_eq_u32_e64 s[4:5], 0, v93
	s_waitcnt lgkmcnt(0)
	v_add_f32_e32 v3, v3, v4
	ds_bpermute_b32 v4, v75, v3
	s_waitcnt lgkmcnt(0)
	v_add_f32_e32 v3, v3, v4
	ds_bpermute_b32 v4, v74, v3
	s_and_saveexec_b64 s[14:15], s[4:5]
	v_readlane_b32 s16, v254, 47
	v_readlane_b32 s28, v254, 34
	s_mov_b32 s36, s38
	v_readlane_b32 s17, v254, 48
	v_readlane_b32 s29, v254, 35
	s_cbranch_execz .LBB0_111
	v_ashrrev_i32_e32 v73, 31, v72
	v_lshlrev_b64 v[6:7], 6, v[72:73]
	v_lshl_add_u64 v[6:7], s[6:7], 0, v[6:7]
	s_waitcnt lgkmcnt(0)
	v_add_f32_e32 v3, v3, v4
	global_store_dword v[6:7], v3, off
